# GEMM epilogues: the eight per-row rms-scale loads issued together at the epilogue head (were laddered load/wait); kmean item loads de-serialised
# baseline (speedup 1.0000x reference)
; __device__ __forceinline__ TileIdx tile_idx() { TileIdx t; t.tid = fresh_tid(); t.wid = t.tid >> 6; t.lane = t.tid & 63; t.wr = t.wid >> 2; t.wc = t.wid & 3; t.fr = t.lane & 15; t.fq = t.lane >> 4; return t; }
; __device__ __forceinline__ float rstd_from_ssq(const float* ssq, int row) {
;     f32x4 s = *(const f32x4*)(ssq + (size_t)row * 4);
;     return rsqrtf((s[0] + s[1] + s[2] + s[3]) * (1.f / 1024.f) + EPS);
; }
; __device__ __forceinline__ void epi_swiglu(Acc& acc, int pm, int pn, const float* ssq, bf16_t* act) {
;     TileIdx t = tile_idx();
;     float rsv[2][4];
; #pragma unroll
;     for (int ai = 0; ai < 2; ++ai)
; #pragma unroll
;         for (int m = 0; m < 4; ++m) rsv[ai][m] = rstd_from_ssq(ssq, pm * 256 + ai * 128 + t.wr * 64 + m * 16 + t.fr);
.LBB0_126:
	v_mov_b32 v1, v179
	s_nop 0
	v_ashrrev_i32_e32 v130, 2, v1
	v_and_b32_e32 v130, 0xffffffc0, v130
	v_and_or_b32 v131, v1, 15, s0
	v_add_u32_e32 v166, v131, v130
	v_add_u32_e32 v172, 0x0, v166
	v_ashrrev_i32_e32 v173, 31, v172
	v_lshl_add_u64 v[172:173], v[172:173], 4, s[22:23]
	global_load_dwordx4 v[174:177], v[172:173], off
	v_add_u32_e32 v172, 0x10, v166
	v_ashrrev_i32_e32 v173, 31, v172
	v_lshl_add_u64 v[172:173], v[172:173], 4, s[22:23]
	global_load_dwordx4 v[184:187], v[172:173], off
	v_add_u32_e32 v172, 0x30, v166
	v_ashrrev_i32_e32 v173, 31, v172
	v_lshl_add_u64 v[172:173], v[172:173], 4, s[22:23]
	global_load_dwordx4 v[188:191], v[172:173], off
	v_add_u32_e32 v172, 0x20, v166
	v_ashrrev_i32_e32 v173, 31, v172
	v_lshl_add_u64 v[172:173], v[172:173], 4, s[22:23]
	global_load_dwordx4 v[204:207], v[172:173], off
	v_add_u32_e32 v172, 0x90, v166
	v_ashrrev_i32_e32 v173, 31, v172
	v_lshl_add_u64 v[172:173], v[172:173], 4, s[22:23]
	global_load_dwordx4 v[208:211], v[172:173], off
	v_add_u32_e32 v172, 0x80, v166
	v_ashrrev_i32_e32 v173, 31, v172
	v_lshl_add_u64 v[172:173], v[172:173], 4, s[22:23]
	global_load_dwordx4 v[212:215], v[172:173], off
	v_add_u32_e32 v172, 0xb0, v166
	v_ashrrev_i32_e32 v173, 31, v172
	v_lshl_add_u64 v[172:173], v[172:173], 4, s[22:23]
	global_load_dwordx4 v[216:219], v[172:173], off
	v_add_u32_e32 v172, 0xa0, v166
	v_ashrrev_i32_e32 v173, 31, v172
	v_lshl_add_u64 v[172:173], v[172:173], 4, s[22:23]
	global_load_dwordx4 v[220:223], v[172:173], off
	s_waitcnt vmcnt(0)
	v_or_b32_e32 v162, 16, v166
	v_ashrrev_i32_e32 v167, 31, v166
	v_ashrrev_i32_e32 v163, 31, v162
	v_lshl_add_u64 v[130:131], v[166:167], 4, s[22:23]
	v_lshl_add_u64 v[134:135], v[162:163], 4, s[22:23]
	v_mov_b32_e32 v130, v174
	v_mov_b32_e32 v131, v175
	v_mov_b32_e32 v132, v176
	v_mov_b32_e32 v133, v177
	s_mov_b32 s0, 0x358637bd
	v_mov_b32_e32 v134, v184
	v_mov_b32_e32 v135, v185
	v_mov_b32_e32 v136, v186
	v_mov_b32_e32 v137, v187
	v_mov_b64_e32 v[168:169], s[0:1]
	v_or_b32_e32 v160, 32, v166
	v_or_b32_e32 v154, 48, v166
	v_ashrrev_i32_e32 v161, 31, v160
	v_ashrrev_i32_e32 v155, 31, v154
	v_add_u32_e32 v152, 0x80, v166
	v_add_u32_e32 v146, 0x90, v166
	v_ashrrev_i32_e32 v153, 31, v152
	v_ashrrev_i32_e32 v147, 31, v146
	v_add_u32_e32 v142, 0xa0, v166
	v_ashrrev_i32_e32 v143, 31, v142
	v_and_b32_e32 v144, 0xc0, v1
	s_waitcnt vmcnt(0)
	v_mov_b32_e32 v139, v130
	v_mov_b32_e32 v138, v134
	v_mov_b32_e32 v130, v135
	v_pk_add_f32 v[130:131], v[138:139], v[130:131]
	v_mov_b32_e32 v134, v136
	v_mov_b32_e32 v135, v132
	v_pk_add_f32 v[130:131], v[134:135], v[130:131]
	v_mov_b32_e32 v132, v137
	v_pk_add_f32 v[130:131], v[132:133], v[130:131]
	v_lshl_add_u64 v[134:135], v[154:155], 4, s[22:23]
	v_pk_fma_f32 v[130:131], v[130:131], s[28:29], v[168:169] op_sel_hi:[1,0,0]
	v_mov_b32_e32 v134, v188
	v_mov_b32_e32 v135, v189
	v_mov_b32_e32 v136, v190
	v_mov_b32_e32 v137, v191
	v_mul_f32_e32 v132, 0x4b800000, v131
	v_cmp_gt_f32_e64 s[0:1], s88, v131
	v_cmp_gt_f32_e32 vcc, s88, v130
	s_waitcnt vmcnt(0)
	v_mov_b32_e32 v138, v134
	v_cndmask_b32_e64 v131, v131, v132, s[0:1]
	v_rsq_f32_e32 v131, v131
	v_mov_b32_e32 v134, v136
	v_mul_f32_e32 v132, 0x45800000, v131
	v_cndmask_b32_e64 v164, v131, v132, s[0:1]
	v_mul_f32_e32 v131, 0x4b800000, v130
	v_cndmask_b32_e32 v130, v130, v131, vcc
	v_rsq_f32_e32 v130, v130
	v_pk_mul_f32 v[122:123], v[122:123], v[164:165] op_sel_hi:[1,0]
	v_pk_mul_f32 v[124:125], v[124:125], v[164:165] op_sel_hi:[1,0]
	v_pk_mul_f32 v[126:127], v[126:127], v[164:165] op_sel_hi:[1,0]
	v_mul_f32_e32 v131, 0x45800000, v130
	v_cndmask_b32_e32 v158, v130, v131, vcc
	v_lshl_add_u64 v[130:131], v[160:161], 4, s[22:23]
	v_mov_b32_e32 v130, v204
	v_mov_b32_e32 v131, v205
	v_mov_b32_e32 v132, v206
	v_mov_b32_e32 v133, v207
	v_pk_mul_f32 v[114:115], v[114:115], v[164:165] op_sel_hi:[1,0]
	v_pk_mul_f32 v[128:129], v[128:129], v[164:165] op_sel_hi:[1,0]
	v_pk_mul_f32 v[116:117], v[116:117], v[164:165] op_sel_hi:[1,0]
	v_pk_mul_f32 v[118:119], v[118:119], v[164:165] op_sel_hi:[1,0]
	v_pk_mul_f32 v[106:107], v[106:107], v[158:159] op_sel_hi:[1,0]
	v_pk_mul_f32 v[120:121], v[120:121], v[164:165] op_sel_hi:[1,0]
	v_pk_mul_f32 v[108:109], v[108:109], v[158:159] op_sel_hi:[1,0]
	v_pk_mul_f32 v[110:111], v[110:111], v[158:159] op_sel_hi:[1,0]
	v_pk_mul_f32 v[98:99], v[98:99], v[158:159] op_sel_hi:[1,0]
	v_pk_mul_f32 v[112:113], v[112:113], v[158:159] op_sel_hi:[1,0]
	v_pk_mul_f32 v[100:101], v[100:101], v[158:159] op_sel_hi:[1,0]
	v_pk_mul_f32 v[102:103], v[102:103], v[158:159] op_sel_hi:[1,0]
	v_pk_mul_f32 v[104:105], v[104:105], v[158:159] op_sel_hi:[1,0]
	s_waitcnt vmcnt(0)
	v_mov_b32_e32 v139, v130
	v_mov_b32_e32 v130, v135
	v_pk_add_f32 v[130:131], v[138:139], v[130:131]
	v_mov_b32_e32 v135, v132
	v_pk_add_f32 v[130:131], v[134:135], v[130:131]
	v_mov_b32_e32 v132, v137
	v_pk_add_f32 v[130:131], v[132:133], v[130:131]
	v_lshl_add_u64 v[134:135], v[146:147], 4, s[22:23]
	v_pk_fma_f32 v[130:131], v[130:131], s[28:29], v[168:169] op_sel_hi:[1,0,0]
	v_mov_b32_e32 v134, v208
	v_mov_b32_e32 v135, v209
	v_mov_b32_e32 v136, v210
	v_mov_b32_e32 v137, v211
	v_mul_f32_e32 v132, 0x4b800000, v131
	v_cmp_gt_f32_e64 s[0:1], s88, v131
	v_cmp_gt_f32_e32 vcc, s88, v130
	s_waitcnt vmcnt(0)
; __device__ __forceinline__ unsigned cvt_pk(float lo, float hi) { f32x2_t v = {lo, hi}; bf16x2_t b = __builtin_convertvector(v, bf16x2_t); return __builtin_bit_cast(unsigned, b); }
; __device__ __forceinline__ float siluf_(float x) { return x * __builtin_amdgcn_rcpf(1.f + __builtin_amdgcn_exp2f(-1.4426950408889634f * x)); }
; __device__ __forceinline__ void epi_swiglu(Acc& acc, int pm, int pn, const float* ssq, bf16_t* act) {
;     ...
;         for (int m = 0; m < 4; ++m) rsv[ai][m] = rstd_from_ssq(ssq, pm * 256 + ai * 128 + t.wr * 64 + m * 16 + t.fr);
; #pragma unroll
;     for (int ai = 0; ai < 2; ++ai)
; #pragma unroll
;         for (int m = 0; m < 4; ++m) {
;             int row = pm * 256 + ai * 128 + t.wr * 64 + m * 16 + t.fr;
;             float rs = rsv[ai][m];
; #pragma unroll
;             for (int n = 0; n < 2; ++n) {
;                 float o[4];
; #pragma unroll
;                 for (int j = 0; j < 4; ++j) { float g = acc[ai][0][m][n][j] * rs, u = acc[ai][1][m][n][j] * rs; o[j] = siluf_(g) * u; }
;                 u32x2 w; w[0] = cvt_pk(o[0], o[1]); w[1] = cvt_pk(o[2], o[3]);
;                 *(u32x2*)(act + (size_t)row * FF + pn * 128 + t.wc * 32 + n * 16 + t.fq * 4) = w;
	v_mov_b32_e32 v138, v134
	v_cndmask_b32_e64 v131, v131, v132, s[0:1]
	v_rsq_f32_e32 v131, v131
	v_mov_b32_e32 v134, v136
	v_mul_f32_e32 v132, 0x45800000, v131
	v_cndmask_b32_e64 v156, v131, v132, s[0:1]
	v_mul_f32_e32 v131, 0x4b800000, v130
	v_cndmask_b32_e32 v130, v130, v131, vcc
	v_rsq_f32_e32 v130, v130
	v_pk_mul_f32 v[90:91], v[90:91], v[156:157] op_sel_hi:[1,0]
	v_pk_mul_f32 v[92:93], v[92:93], v[156:157] op_sel_hi:[1,0]
	v_pk_mul_f32 v[94:95], v[94:95], v[156:157] op_sel_hi:[1,0]
	v_mul_f32_e32 v131, 0x45800000, v130
	v_cndmask_b32_e32 v150, v130, v131, vcc
	v_lshl_add_u64 v[130:131], v[152:153], 4, s[22:23]
	v_mov_b32_e32 v130, v212
	v_mov_b32_e32 v131, v213
	v_mov_b32_e32 v132, v214
	v_mov_b32_e32 v133, v215
	v_pk_mul_f32 v[82:83], v[82:83], v[156:157] op_sel_hi:[1,0]
	v_pk_mul_f32 v[96:97], v[96:97], v[156:157] op_sel_hi:[1,0]
	v_pk_mul_f32 v[84:85], v[84:85], v[156:157] op_sel_hi:[1,0]
	v_pk_mul_f32 v[86:87], v[86:87], v[156:157] op_sel_hi:[1,0]
	v_pk_mul_f32 v[74:75], v[74:75], v[150:151] op_sel_hi:[1,0]
	v_pk_mul_f32 v[88:89], v[88:89], v[156:157] op_sel_hi:[1,0]
	v_pk_mul_f32 v[76:77], v[76:77], v[150:151] op_sel_hi:[1,0]
	v_pk_mul_f32 v[78:79], v[78:79], v[150:151] op_sel_hi:[1,0]
	v_pk_mul_f32 v[66:67], v[66:67], v[150:151] op_sel_hi:[1,0]
	v_pk_mul_f32 v[80:81], v[80:81], v[150:151] op_sel_hi:[1,0]
	v_pk_mul_f32 v[68:69], v[68:69], v[150:151] op_sel_hi:[1,0]
	v_pk_mul_f32 v[70:71], v[70:71], v[150:151] op_sel_hi:[1,0]
	v_pk_mul_f32 v[72:73], v[72:73], v[150:151] op_sel_hi:[1,0]
	s_waitcnt vmcnt(0)
	v_mov_b32_e32 v139, v130
	v_mov_b32_e32 v130, v135
	v_pk_add_f32 v[130:131], v[138:139], v[130:131]
	v_mov_b32_e32 v135, v132
	v_pk_add_f32 v[130:131], v[134:135], v[130:131]
	v_mov_b32_e32 v132, v137
	v_pk_add_f32 v[130:131], v[132:133], v[130:131]
	v_add_u32_e32 v138, 0xb0, v166
	v_pk_fma_f32 v[130:131], v[130:131], s[28:29], v[168:169] op_sel_hi:[1,0,0]
	v_ashrrev_i32_e32 v139, 31, v138
	v_mul_f32_e32 v132, 0x4b800000, v131
	v_cmp_gt_f32_e64 s[0:1], s88, v131
	v_cmp_gt_f32_e32 vcc, s88, v130
	v_lshl_add_u64 v[134:135], v[138:139], 4, s[22:23]
	v_cndmask_b32_e64 v131, v131, v132, s[0:1]
	v_rsq_f32_e32 v131, v131
	v_mov_b32_e32 v134, v216
	v_mov_b32_e32 v135, v217
	v_mov_b32_e32 v136, v218
	v_mov_b32_e32 v137, v219
	v_mul_f32_e32 v132, 0x45800000, v131
	v_cndmask_b32_e64 v148, v131, v132, s[0:1]
	v_mul_f32_e32 v131, 0x4b800000, v130
	v_cndmask_b32_e32 v130, v130, v131, vcc
	v_rsq_f32_e32 v130, v130
	v_pk_mul_f32 v[58:59], v[58:59], v[148:149] op_sel_hi:[1,0]
	v_pk_mul_f32 v[60:61], v[60:61], v[148:149] op_sel_hi:[1,0]
	v_pk_mul_f32 v[62:63], v[62:63], v[148:149] op_sel_hi:[1,0]
	v_mul_f32_e32 v131, 0x45800000, v130
	v_cndmask_b32_e32 v140, v130, v131, vcc
	v_lshl_add_u64 v[130:131], v[142:143], 4, s[22:23]
	v_mov_b32_e32 v130, v220
	v_mov_b32_e32 v131, v221
	v_mov_b32_e32 v132, v222
	v_mov_b32_e32 v133, v223
	v_pk_mul_f32 v[50:51], v[50:51], v[148:149] op_sel_hi:[1,0]
	v_pk_mul_f32 v[64:65], v[64:65], v[148:149] op_sel_hi:[1,0]
	v_pk_mul_f32 v[52:53], v[52:53], v[148:149] op_sel_hi:[1,0]
	v_pk_mul_f32 v[54:55], v[54:55], v[148:149] op_sel_hi:[1,0]
	v_pk_mul_f32 v[42:43], v[42:43], v[140:141] op_sel_hi:[1,0]
	v_pk_mul_f32 v[56:57], v[56:57], v[148:149] op_sel_hi:[1,0]
	v_pk_mul_f32 v[44:45], v[44:45], v[140:141] op_sel_hi:[1,0]
	v_pk_mul_f32 v[46:47], v[46:47], v[140:141] op_sel_hi:[1,0]
	v_pk_mul_f32 v[34:35], v[34:35], v[140:141] op_sel_hi:[1,0]
	v_pk_mul_f32 v[48:49], v[48:49], v[140:141] op_sel_hi:[1,0]
	v_pk_mul_f32 v[36:37], v[36:37], v[140:141] op_sel_hi:[1,0]
	v_pk_mul_f32 v[38:39], v[38:39], v[140:141] op_sel_hi:[1,0]
	v_pk_mul_f32 v[40:41], v[40:41], v[140:141] op_sel_hi:[1,0]
	s_waitcnt vmcnt(0)
	v_mov_b32_e32 v170, v134
	v_mov_b32_e32 v134, v136
	v_mov_b32_e32 v171, v130
	v_mov_b32_e32 v130, v135
	v_pk_add_f32 v[130:131], v[170:171], v[130:131]
	v_mov_b32_e32 v135, v132
	v_pk_add_f32 v[130:131], v[134:135], v[130:131]
	v_mov_b32_e32 v132, v137
	v_pk_add_f32 v[130:131], v[132:133], v[130:131]
	s_nop 0
	v_pk_fma_f32 v[130:131], v[130:131], s[28:29], v[168:169] op_sel_hi:[1,0,0]
	s_nop 0
	v_mul_f32_e32 v132, 0x4b800000, v131
	v_cmp_gt_f32_e64 s[0:1], s88, v131
	v_cmp_gt_f32_e32 vcc, s88, v130
	s_nop 0
	v_cndmask_b32_e64 v131, v131, v132, s[0:1]
	v_rsq_f32_e32 v131, v131
	s_nop 0
	v_mul_f32_e32 v132, 0x45800000, v131
	v_cndmask_b32_e64 v134, v131, v132, s[0:1]
	v_mul_f32_e32 v131, 0x4b800000, v130
	v_cndmask_b32_e32 v130, v130, v131, vcc
	v_rsq_f32_e32 v130, v130
	s_lshl_b32 s0, s56, 7
	s_ashr_i32 s1, s0, 31
	s_lshl_b64 s[0:1], s[0:1], 1
	v_mul_f32_e32 v131, 0x45800000, v130
	v_cndmask_b32_e32 v130, v130, v131, vcc
	v_lshrrev_b32_e32 v131, 1, v1
	v_mul_f32_e32 v1, 0xbfb8aa3b, v122
	v_exp_f32_e32 v1, v1
	s_add_u32 s0, s18, s0
	s_addc_u32 s1, s19, s1
	v_lshl_add_u64 v[132:133], s[0:1], 0, v[144:145]
	v_and_b32_e32 v144, 24, v131
	v_lshl_add_u64 v[132:133], v[132:133], 0, v[144:145]
	v_add_f32_e32 v1, 1.0, v1
	v_mad_i64_i32 v[136:137], s[0:1], v166, s89, v[132:133]
	v_rcp_f32_e32 v166, v1
	v_mul_f32_e32 v1, 0xbfb8aa3b, v123
	v_exp_f32_e32 v1, v1
	v_pk_mul_f32 v[26:27], v[26:27], v[134:135] op_sel_hi:[1,0]
	v_pk_mul_f32 v[28:29], v[28:29], v[134:135] op_sel_hi:[1,0]
	v_pk_mul_f32 v[30:31], v[30:31], v[134:135] op_sel_hi:[1,0]
	v_add_f32_e32 v1, 1.0, v1
	v_rcp_f32_e32 v167, v1
	v_mul_f32_e32 v1, 0xbfb8aa3b, v124
	v_exp_f32_e32 v1, v1
	v_pk_mul_f32 v[18:19], v[18:19], v[134:135] op_sel_hi:[1,0]
	v_pk_mul_f32 v[122:123], v[122:123], v[166:167]
	v_pk_mul_f32 v[32:33], v[32:33], v[134:135] op_sel_hi:[1,0]
	v_add_f32_e32 v1, 1.0, v1
	v_pk_mul_f32 v[122:123], v[126:127], v[122:123]
	v_rcp_f32_e32 v126, v1
	v_mul_f32_e32 v1, 0xbfb8aa3b, v125
; __device__ __forceinline__ unsigned cvt_pk(float lo, float hi) { f32x2_t v = {lo, hi}; bf16x2_t b = __builtin_convertvector(v, bf16x2_t); return __builtin_bit_cast(unsigned, b); }
; __device__ __forceinline__ float siluf_(float x) { return x * __builtin_amdgcn_rcpf(1.f + __builtin_amdgcn_exp2f(-1.4426950408889634f * x)); }
; __device__ __forceinline__ void epi_swiglu(Acc& acc, int pm, int pn, const float* ssq, bf16_t* act) {
;     ...
;             for (int n = 0; n < 2; ++n) {
;                 float o[4];
; #pragma unroll
;                 for (int j = 0; j < 4; ++j) { float g = acc[ai][0][m][n][j] * rs, u = acc[ai][1][m][n][j] * rs; o[j] = siluf_(g) * u; }
;                 u32x2 w; w[0] = cvt_pk(o[0], o[1]); w[1] = cvt_pk(o[2], o[3]);
;                 *(u32x2*)(act + (size_t)row * FF + pn * 128 + t.wc * 32 + n * 16 + t.fq * 4) = w;
;             }
	v_exp_f32_e32 v1, v1
	v_cvt_pk_bf16_f32 v122, v122, v123
	v_pk_mul_f32 v[20:21], v[20:21], v[134:135] op_sel_hi:[1,0]
	v_pk_mul_f32 v[22:23], v[22:23], v[134:135] op_sel_hi:[1,0]
	v_add_f32_e32 v1, 1.0, v1
	v_rcp_f32_e32 v127, v1
	v_mul_f32_e32 v1, 0xbfb8aa3b, v114
	v_exp_f32_e32 v1, v1
	v_pk_mul_f32 v[10:11], v[10:11], v[130:131] op_sel_hi:[1,0]
	v_pk_mul_f32 v[124:125], v[124:125], v[126:127]
	v_pk_mul_f32 v[24:25], v[24:25], v[134:135] op_sel_hi:[1,0]
	v_pk_mul_f32 v[124:125], v[128:129], v[124:125]
	v_add_f32_e32 v1, 1.0, v1
	v_cvt_pk_bf16_f32 v123, v124, v125
	global_store_dwordx2 v[136:137], v[122:123], off
	v_rcp_f32_e32 v122, v1
	v_mul_f32_e32 v1, 0xbfb8aa3b, v115
	v_exp_f32_e32 v1, v1
	v_pk_mul_f32 v[12:13], v[12:13], v[130:131] op_sel_hi:[1,0]
	v_pk_mul_f32 v[14:15], v[14:15], v[130:131] op_sel_hi:[1,0]
	v_pk_mul_f32 v[2:3], v[2:3], v[130:131] op_sel_hi:[1,0]
	v_add_f32_e32 v1, 1.0, v1
	v_rcp_f32_e32 v123, v1
	v_mul_f32_e32 v1, 0xbfb8aa3b, v116
	v_exp_f32_e32 v1, v1
	v_pk_mul_f32 v[16:17], v[16:17], v[130:131] op_sel_hi:[1,0]
	v_pk_mul_f32 v[114:115], v[114:115], v[122:123]
	v_pk_mul_f32 v[4:5], v[4:5], v[130:131] op_sel_hi:[1,0]
	v_add_f32_e32 v1, 1.0, v1
	v_pk_mul_f32 v[114:115], v[118:119], v[114:115]
	v_rcp_f32_e32 v118, v1
	v_mul_f32_e32 v1, 0xbfb8aa3b, v117
	v_exp_f32_e32 v1, v1
	v_cvt_pk_bf16_f32 v114, v114, v115
	v_pk_mul_f32 v[6:7], v[6:7], v[130:131] op_sel_hi:[1,0]
	v_pk_mul_f32 v[8:9], v[8:9], v[130:131] op_sel_hi:[1,0]
	v_add_f32_e32 v1, 1.0, v1
	v_rcp_f32_e32 v119, v1
	v_mul_f32_e32 v1, 0xbfb8aa3b, v106
	v_exp_f32_e32 v1, v1
	s_and_b64 vcc, exec, s[12:13]
	v_pk_mul_f32 v[116:117], v[116:117], v[118:119]
	v_add_f32_e32 v1, 1.0, v1
	v_pk_mul_f32 v[116:117], v[120:121], v[116:117]
	s_nop 0
	v_cvt_pk_bf16_f32 v115, v116, v117
	v_rcp_f32_e32 v116, v1
	v_mul_f32_e32 v1, 0xbfb8aa3b, v107
	v_exp_f32_e32 v1, v1
	global_store_dwordx2 v[136:137], v[114:115], off offset:32
	v_mad_i64_i32 v[114:115], s[0:1], v162, s89, v[132:133]
	v_add_f32_e32 v1, 1.0, v1
	v_rcp_f32_e32 v117, v1
	v_mul_f32_e32 v1, 0xbfb8aa3b, v108
	v_exp_f32_e32 v1, v1
	v_pk_mul_f32 v[106:107], v[106:107], v[116:117]
	s_nop 0
	v_pk_mul_f32 v[106:107], v[110:111], v[106:107]
	v_add_f32_e32 v1, 1.0, v1
	v_rcp_f32_e32 v110, v1
	v_mul_f32_e32 v1, 0xbfb8aa3b, v109
	v_exp_f32_e32 v1, v1
	v_cvt_pk_bf16_f32 v106, v106, v107
	v_add_f32_e32 v1, 1.0, v1
	v_rcp_f32_e32 v111, v1
	v_mul_f32_e32 v1, 0xbfb8aa3b, v98
	v_exp_f32_e32 v1, v1
	v_pk_mul_f32 v[108:109], v[108:109], v[110:111]
	s_nop 0
	v_pk_mul_f32 v[108:109], v[112:113], v[108:109]
	v_add_f32_e32 v1, 1.0, v1
	v_cvt_pk_bf16_f32 v107, v108, v109
	global_store_dwordx2 v[114:115], v[106:107], off
	v_rcp_f32_e32 v106, v1
	v_mul_f32_e32 v1, 0xbfb8aa3b, v99
	v_exp_f32_e32 v1, v1
	s_nop 0
	v_add_f32_e32 v1, 1.0, v1
	v_rcp_f32_e32 v107, v1
	v_mul_f32_e32 v1, 0xbfb8aa3b, v100
	v_exp_f32_e32 v1, v1
	v_pk_mul_f32 v[98:99], v[98:99], v[106:107]
	s_nop 0
	v_pk_mul_f32 v[98:99], v[102:103], v[98:99]
	v_add_f32_e32 v1, 1.0, v1
	v_rcp_f32_e32 v102, v1
	v_mul_f32_e32 v1, 0xbfb8aa3b, v101
	v_exp_f32_e32 v1, v1
	v_cvt_pk_bf16_f32 v98, v98, v99
	v_add_f32_e32 v1, 1.0, v1
	v_rcp_f32_e32 v103, v1
	v_mul_f32_e32 v1, 0xbfb8aa3b, v90
	v_exp_f32_e32 v1, v1
	v_pk_mul_f32 v[100:101], v[100:101], v[102:103]
	s_nop 0
	v_pk_mul_f32 v[100:101], v[104:105], v[100:101]
	v_add_f32_e32 v1, 1.0, v1
	v_cvt_pk_bf16_f32 v99, v100, v101
	v_rcp_f32_e32 v100, v1
	v_mul_f32_e32 v1, 0xbfb8aa3b, v91
	v_exp_f32_e32 v1, v1
	global_store_dwordx2 v[114:115], v[98:99], off offset:32
	v_mad_i64_i32 v[98:99], s[0:1], v160, s89, v[132:133]
	v_add_f32_e32 v1, 1.0, v1
	v_rcp_f32_e32 v101, v1
	v_mul_f32_e32 v1, 0xbfb8aa3b, v92
	v_exp_f32_e32 v1, v1
	v_pk_mul_f32 v[90:91], v[90:91], v[100:101]
	s_nop 0
	v_pk_mul_f32 v[90:91], v[94:95], v[90:91]
	v_add_f32_e32 v1, 1.0, v1
	v_rcp_f32_e32 v94, v1
	v_mul_f32_e32 v1, 0xbfb8aa3b, v93
	v_exp_f32_e32 v1, v1
	v_cvt_pk_bf16_f32 v90, v90, v91
	v_add_f32_e32 v1, 1.0, v1
	v_rcp_f32_e32 v95, v1
	v_mul_f32_e32 v1, 0xbfb8aa3b, v82
	v_exp_f32_e32 v1, v1
	v_pk_mul_f32 v[92:93], v[92:93], v[94:95]
	s_nop 0
	v_pk_mul_f32 v[92:93], v[96:97], v[92:93]
	v_add_f32_e32 v1, 1.0, v1
	v_cvt_pk_bf16_f32 v91, v92, v93
	global_store_dwordx2 v[98:99], v[90:91], off
	v_rcp_f32_e32 v90, v1
	v_mul_f32_e32 v1, 0xbfb8aa3b, v83
	v_exp_f32_e32 v1, v1
	s_nop 0
	v_add_f32_e32 v1, 1.0, v1
	v_rcp_f32_e32 v91, v1
	v_mul_f32_e32 v1, 0xbfb8aa3b, v84
	v_exp_f32_e32 v1, v1
	v_pk_mul_f32 v[82:83], v[82:83], v[90:91]
	s_nop 0
	v_pk_mul_f32 v[82:83], v[86:87], v[82:83]
	v_add_f32_e32 v1, 1.0, v1
	v_rcp_f32_e32 v86, v1
	v_mul_f32_e32 v1, 0xbfb8aa3b, v85
	v_exp_f32_e32 v1, v1
	v_cvt_pk_bf16_f32 v82, v82, v83
	v_add_f32_e32 v1, 1.0, v1
	v_rcp_f32_e32 v87, v1
	v_mul_f32_e32 v1, 0xbfb8aa3b, v74
	v_exp_f32_e32 v1, v1
	v_pk_mul_f32 v[84:85], v[84:85], v[86:87]
	s_nop 0
	v_pk_mul_f32 v[84:85], v[88:89], v[84:85]
	v_add_f32_e32 v1, 1.0, v1
	v_cvt_pk_bf16_f32 v83, v84, v85
	v_rcp_f32_e32 v84, v1
	v_mul_f32_e32 v1, 0xbfb8aa3b, v75
	v_exp_f32_e32 v1, v1
	global_store_dwordx2 v[98:99], v[82:83], off offset:32
	v_mad_i64_i32 v[82:83], s[0:1], v154, s89, v[132:133]
	v_add_f32_e32 v1, 1.0, v1
	v_rcp_f32_e32 v85, v1
	v_mul_f32_e32 v1, 0xbfb8aa3b, v76
	v_exp_f32_e32 v1, v1
	v_pk_mul_f32 v[74:75], v[74:75], v[84:85]
	s_nop 0
	v_pk_mul_f32 v[74:75], v[78:79], v[74:75]
	v_add_f32_e32 v1, 1.0, v1
	v_rcp_f32_e32 v78, v1
	v_mul_f32_e32 v1, 0xbfb8aa3b, v77
	v_exp_f32_e32 v1, v1
	v_cvt_pk_bf16_f32 v74, v74, v75
	v_add_f32_e32 v1, 1.0, v1
	v_rcp_f32_e32 v79, v1
	v_mul_f32_e32 v1, 0xbfb8aa3b, v66
	v_exp_f32_e32 v1, v1
	v_pk_mul_f32 v[76:77], v[76:77], v[78:79]
	s_nop 0
	v_pk_mul_f32 v[76:77], v[80:81], v[76:77]
; __device__ __forceinline__ unsigned cvt_pk(float lo, float hi) { f32x2_t v = {lo, hi}; bf16x2_t b = __builtin_convertvector(v, bf16x2_t); return __builtin_bit_cast(unsigned, b); }
; __device__ __forceinline__ float siluf_(float x) { return x * __builtin_amdgcn_rcpf(1.f + __builtin_amdgcn_exp2f(-1.4426950408889634f * x)); }
; __device__ __forceinline__ void epi_swiglu(Acc& acc, int pm, int pn, const float* ssq, bf16_t* act) {
;     ...
;             for (int n = 0; n < 2; ++n) {
;                 float o[4];
; #pragma unroll
;                 for (int j = 0; j < 4; ++j) { float g = acc[ai][0][m][n][j] * rs, u = acc[ai][1][m][n][j] * rs; o[j] = siluf_(g) * u; }
;                 u32x2 w; w[0] = cvt_pk(o[0], o[1]); w[1] = cvt_pk(o[2], o[3]);
;                 *(u32x2*)(act + (size_t)row * FF + pn * 128 + t.wc * 32 + n * 16 + t.fq * 4) = w;
;             }
; __device__ __forceinline__ void phase_ffn1(const Ctx& a, const bf16_t* W, LAS unsigned char* lds) {
;     ...
;         __syncthreads();
	v_add_f32_e32 v1, 1.0, v1
	v_cvt_pk_bf16_f32 v75, v76, v77
	global_store_dwordx2 v[82:83], v[74:75], off
	v_rcp_f32_e32 v74, v1
	v_mul_f32_e32 v1, 0xbfb8aa3b, v67
	v_exp_f32_e32 v1, v1
	s_nop 0
	v_add_f32_e32 v1, 1.0, v1
	v_rcp_f32_e32 v75, v1
	v_mul_f32_e32 v1, 0xbfb8aa3b, v68
	v_exp_f32_e32 v1, v1
	v_pk_mul_f32 v[66:67], v[66:67], v[74:75]
	s_nop 0
	v_pk_mul_f32 v[66:67], v[70:71], v[66:67]
	v_add_f32_e32 v1, 1.0, v1
	v_rcp_f32_e32 v70, v1
	v_mul_f32_e32 v1, 0xbfb8aa3b, v69
	v_exp_f32_e32 v1, v1
	v_cvt_pk_bf16_f32 v66, v66, v67
	v_add_f32_e32 v1, 1.0, v1
	v_rcp_f32_e32 v71, v1
	v_mul_f32_e32 v1, 0xbfb8aa3b, v58
	v_exp_f32_e32 v1, v1
	v_pk_mul_f32 v[68:69], v[68:69], v[70:71]
	s_nop 0
	v_pk_mul_f32 v[68:69], v[72:73], v[68:69]
	v_add_f32_e32 v1, 1.0, v1
	v_cvt_pk_bf16_f32 v67, v68, v69
	v_rcp_f32_e32 v68, v1
	v_mul_f32_e32 v1, 0xbfb8aa3b, v59
	v_exp_f32_e32 v1, v1
	global_store_dwordx2 v[82:83], v[66:67], off offset:32
	v_mad_i64_i32 v[66:67], s[0:1], v152, s89, v[132:133]
	v_add_f32_e32 v1, 1.0, v1
	v_rcp_f32_e32 v69, v1
	v_mul_f32_e32 v1, 0xbfb8aa3b, v60
	v_exp_f32_e32 v1, v1
	v_pk_mul_f32 v[58:59], v[58:59], v[68:69]
	s_nop 0
	v_pk_mul_f32 v[58:59], v[62:63], v[58:59]
	v_add_f32_e32 v1, 1.0, v1
	v_rcp_f32_e32 v62, v1
	v_mul_f32_e32 v1, 0xbfb8aa3b, v61
	v_exp_f32_e32 v1, v1
	v_cvt_pk_bf16_f32 v58, v58, v59
	v_add_f32_e32 v1, 1.0, v1
	v_rcp_f32_e32 v63, v1
	v_mul_f32_e32 v1, 0xbfb8aa3b, v50
	v_exp_f32_e32 v1, v1
	v_pk_mul_f32 v[60:61], v[60:61], v[62:63]
	s_nop 0
	v_pk_mul_f32 v[60:61], v[64:65], v[60:61]
	v_add_f32_e32 v1, 1.0, v1
	v_cvt_pk_bf16_f32 v59, v60, v61
	global_store_dwordx2 v[66:67], v[58:59], off
	v_rcp_f32_e32 v58, v1
	v_mul_f32_e32 v1, 0xbfb8aa3b, v51
	v_exp_f32_e32 v1, v1
	s_nop 0
	v_add_f32_e32 v1, 1.0, v1
	v_rcp_f32_e32 v59, v1
	v_mul_f32_e32 v1, 0xbfb8aa3b, v52
	v_exp_f32_e32 v1, v1
	v_pk_mul_f32 v[50:51], v[50:51], v[58:59]
	s_nop 0
	v_pk_mul_f32 v[50:51], v[54:55], v[50:51]
	v_add_f32_e32 v1, 1.0, v1
	v_rcp_f32_e32 v54, v1
	v_mul_f32_e32 v1, 0xbfb8aa3b, v53
	v_exp_f32_e32 v1, v1
	v_cvt_pk_bf16_f32 v50, v50, v51
	v_add_f32_e32 v1, 1.0, v1
	v_rcp_f32_e32 v55, v1
	v_mul_f32_e32 v1, 0xbfb8aa3b, v42
	v_exp_f32_e32 v1, v1
	v_pk_mul_f32 v[52:53], v[52:53], v[54:55]
	s_nop 0
	v_pk_mul_f32 v[52:53], v[56:57], v[52:53]
	v_add_f32_e32 v1, 1.0, v1
	v_cvt_pk_bf16_f32 v51, v52, v53
	v_rcp_f32_e32 v52, v1
	v_mul_f32_e32 v1, 0xbfb8aa3b, v43
	v_exp_f32_e32 v1, v1
	global_store_dwordx2 v[66:67], v[50:51], off offset:32
	v_mad_i64_i32 v[50:51], s[0:1], v146, s89, v[132:133]
	v_add_f32_e32 v1, 1.0, v1
	v_rcp_f32_e32 v53, v1
	v_mul_f32_e32 v1, 0xbfb8aa3b, v44
	v_exp_f32_e32 v1, v1
	v_pk_mul_f32 v[42:43], v[42:43], v[52:53]
	s_nop 0
	v_pk_mul_f32 v[42:43], v[46:47], v[42:43]
	v_add_f32_e32 v1, 1.0, v1
	v_rcp_f32_e32 v46, v1
	v_mul_f32_e32 v1, 0xbfb8aa3b, v45
	v_exp_f32_e32 v1, v1
	v_cvt_pk_bf16_f32 v42, v42, v43
	v_add_f32_e32 v1, 1.0, v1
	v_rcp_f32_e32 v47, v1
	v_mul_f32_e32 v1, 0xbfb8aa3b, v34
	v_exp_f32_e32 v1, v1
	v_pk_mul_f32 v[44:45], v[44:45], v[46:47]
	s_nop 0
	v_pk_mul_f32 v[44:45], v[48:49], v[44:45]
	v_add_f32_e32 v1, 1.0, v1
	v_cvt_pk_bf16_f32 v43, v44, v45
	global_store_dwordx2 v[50:51], v[42:43], off
	v_rcp_f32_e32 v42, v1
	v_mul_f32_e32 v1, 0xbfb8aa3b, v35
	v_exp_f32_e32 v1, v1
	s_nop 0
	v_add_f32_e32 v1, 1.0, v1
	v_rcp_f32_e32 v43, v1
	v_mul_f32_e32 v1, 0xbfb8aa3b, v36
	v_exp_f32_e32 v1, v1
	v_pk_mul_f32 v[34:35], v[34:35], v[42:43]
	s_nop 0
	v_pk_mul_f32 v[34:35], v[38:39], v[34:35]
	v_add_f32_e32 v1, 1.0, v1
	v_rcp_f32_e32 v38, v1
	v_mul_f32_e32 v1, 0xbfb8aa3b, v37
	v_exp_f32_e32 v1, v1
	v_cvt_pk_bf16_f32 v34, v34, v35
	v_add_f32_e32 v1, 1.0, v1
	v_rcp_f32_e32 v39, v1
	v_mul_f32_e32 v1, 0xbfb8aa3b, v26
	v_exp_f32_e32 v1, v1
	v_pk_mul_f32 v[36:37], v[36:37], v[38:39]
	s_nop 0
	v_pk_mul_f32 v[36:37], v[40:41], v[36:37]
	v_add_f32_e32 v1, 1.0, v1
	v_cvt_pk_bf16_f32 v35, v36, v37
	v_rcp_f32_e32 v36, v1
	v_mul_f32_e32 v1, 0xbfb8aa3b, v27
	v_exp_f32_e32 v1, v1
	global_store_dwordx2 v[50:51], v[34:35], off offset:32
	v_mad_i64_i32 v[34:35], s[0:1], v142, s89, v[132:133]
	v_add_f32_e32 v1, 1.0, v1
	v_rcp_f32_e32 v37, v1
	v_mul_f32_e32 v1, 0xbfb8aa3b, v28
	v_exp_f32_e32 v1, v1
	v_pk_mul_f32 v[26:27], v[26:27], v[36:37]
	s_nop 0
	v_pk_mul_f32 v[26:27], v[30:31], v[26:27]
	v_add_f32_e32 v1, 1.0, v1
	v_rcp_f32_e32 v30, v1
	v_mul_f32_e32 v1, 0xbfb8aa3b, v29
	v_exp_f32_e32 v1, v1
	v_cvt_pk_bf16_f32 v26, v26, v27
	v_add_f32_e32 v1, 1.0, v1
	v_rcp_f32_e32 v31, v1
	v_mul_f32_e32 v1, 0xbfb8aa3b, v18
	v_exp_f32_e32 v1, v1
	v_pk_mul_f32 v[28:29], v[28:29], v[30:31]
	s_nop 0
	v_pk_mul_f32 v[28:29], v[32:33], v[28:29]
	v_add_f32_e32 v1, 1.0, v1
	v_cvt_pk_bf16_f32 v27, v28, v29
	global_store_dwordx2 v[34:35], v[26:27], off
	v_rcp_f32_e32 v26, v1
	v_mul_f32_e32 v1, 0xbfb8aa3b, v19
	v_exp_f32_e32 v1, v1
	s_nop 0
	v_add_f32_e32 v1, 1.0, v1
	v_rcp_f32_e32 v27, v1
	v_mul_f32_e32 v1, 0xbfb8aa3b, v20
	v_exp_f32_e32 v1, v1
	v_pk_mul_f32 v[18:19], v[18:19], v[26:27]
	s_nop 0
	v_pk_mul_f32 v[18:19], v[22:23], v[18:19]
	v_add_f32_e32 v1, 1.0, v1
	v_rcp_f32_e32 v22, v1
	v_mul_f32_e32 v1, 0xbfb8aa3b, v21
	v_exp_f32_e32 v1, v1
	v_cvt_pk_bf16_f32 v18, v18, v19
	v_add_f32_e32 v1, 1.0, v1
	v_rcp_f32_e32 v23, v1
	v_mul_f32_e32 v1, 0xbfb8aa3b, v10
	v_exp_f32_e32 v1, v1
	v_pk_mul_f32 v[20:21], v[20:21], v[22:23]
	s_nop 0
	v_pk_mul_f32 v[20:21], v[24:25], v[20:21]
	v_add_f32_e32 v1, 1.0, v1
	v_cvt_pk_bf16_f32 v19, v20, v21
	v_rcp_f32_e32 v20, v1
	v_mul_f32_e32 v1, 0xbfb8aa3b, v11
	v_exp_f32_e32 v1, v1
	global_store_dwordx2 v[34:35], v[18:19], off offset:32
	v_mad_i64_i32 v[18:19], s[0:1], v138, s89, v[132:133]
	v_add_f32_e32 v1, 1.0, v1
	v_rcp_f32_e32 v21, v1
	v_mul_f32_e32 v1, 0xbfb8aa3b, v12
	v_exp_f32_e32 v1, v1
	v_pk_mul_f32 v[10:11], v[10:11], v[20:21]
	s_nop 0
	v_pk_mul_f32 v[10:11], v[14:15], v[10:11]
	v_add_f32_e32 v1, 1.0, v1
	v_rcp_f32_e32 v14, v1
	v_mul_f32_e32 v1, 0xbfb8aa3b, v13
	v_exp_f32_e32 v1, v1
	v_cvt_pk_bf16_f32 v10, v10, v11
	v_add_f32_e32 v1, 1.0, v1
	v_rcp_f32_e32 v15, v1
	v_mul_f32_e32 v1, 0xbfb8aa3b, v2
	v_exp_f32_e32 v1, v1
	v_pk_mul_f32 v[12:13], v[12:13], v[14:15]
	s_nop 0
	v_pk_mul_f32 v[12:13], v[16:17], v[12:13]
	v_add_f32_e32 v1, 1.0, v1
	v_cvt_pk_bf16_f32 v11, v12, v13
	global_store_dwordx2 v[18:19], v[10:11], off
	v_rcp_f32_e32 v10, v1
	v_mul_f32_e32 v1, 0xbfb8aa3b, v3
	v_exp_f32_e32 v1, v1
	s_nop 0
	v_add_f32_e32 v1, 1.0, v1
	v_rcp_f32_e32 v11, v1
	v_mul_f32_e32 v1, 0xbfb8aa3b, v4
	v_exp_f32_e32 v1, v1
	v_pk_mul_f32 v[2:3], v[2:3], v[10:11]
	s_nop 0
	v_pk_mul_f32 v[2:3], v[6:7], v[2:3]
	v_add_f32_e32 v1, 1.0, v1
	v_rcp_f32_e32 v6, v1
	v_mul_f32_e32 v1, 0xbfb8aa3b, v5
	v_exp_f32_e32 v1, v1
	v_cvt_pk_bf16_f32 v2, v2, v3
	v_add_f32_e32 v1, 1.0, v1
	v_rcp_f32_e32 v7, v1
	s_nop 0
	v_pk_mul_f32 v[4:5], v[4:5], v[6:7]
	s_nop 0
	v_pk_mul_f32 v[4:5], v[8:9], v[4:5]
	s_nop 0
	v_cvt_pk_bf16_f32 v3, v4, v5
	global_store_dwordx2 v[18:19], v[2:3], off offset:32
	s_waitcnt lgkmcnt(0)
	s_barrier
	s_cbranch_vccnz .LBB0_123

; __device__ __forceinline__ float bf2f(bf16_t h) { return __uint_as_float(((unsigned)h) << 16); }
; __device__ __forceinline__ int fresh_tid() { int t; asm volatile("v_mov_b32 %0, %1" : "=v"(t) : "v"(threadIdx.x)); return t; }
; __device__ __forceinline__ int fresh_bid() { int t; asm volatile("s_mov_b32 %0, %1" : "=s"(t) : "s"(blockIdx.x)); return t; }
; __device__ __forceinline__ void kmean_items(const Ctx& a, LAS unsigned char* lds) {
;     ...
;     for (int it = fresh_bid(); it < 256; it += gridDim.x) {
;         int hh = it >> 5, n = it & 31, d = fresh_tid() & 63, tg = fresh_tid() >> 6;
;         float s = 0.f;
;         for (int i = 0; i < 32; ++i) s += bf2f(pa[(size_t)(n * 256 + tg * 32 + i) * PA + C_MK + hh * 64 + d]);
;         part[tg * 64 + d] = s;
.LBB0_332:
	s_cmpk_gt_i32 s0, 0xff
	s_cbranch_scc1 .LBB0_335
	v_mov_b32 v1, v179
	s_waitcnt vmcnt(0) lgkmcnt(0)
	v_mov_b32 v6, v179
	s_lshl_b32 s1, s0, 8
	v_ashrrev_i32_e32 v2, 1, v6
	s_and_b32 s1, s1, 0x1f00
	v_and_b32_e32 v2, 0xffffffe0, v2
	v_add_u32_e32 v2, s1, v2
	s_lshl_b32 s1, s0, 1
	s_and_b32 s12, s1, 0xffffffc0
	s_ashr_i32 s13, s12, 31
	s_lshl_b64 s[12:13], s[12:13], 1
	v_readlane_b32 s1, v254, 40
	v_and_b32_e32 v1, 63, v1
	s_add_u32 s12, s1, s12
	v_readlane_b32 s1, v254, 41
	s_addc_u32 s13, s1, s13
	v_lshlrev_b32_e32 v144, 1, v1
	v_ashrrev_i32_e32 v3, 31, v2
	v_lshl_add_u64 v[4:5], s[12:13], 0, v[144:145]
	v_lshlrev_b64 v[8:9], 13, v[2:3]
	v_lshl_add_u64 v[8:9], v[4:5], 0, v[8:9]
	global_load_ushort v34, v[8:9], off
	v_or_b32_e32 v8, 1, v2
	v_ashrrev_i32_e32 v9, 31, v8
	v_lshlrev_b64 v[8:9], 13, v[8:9]
	v_lshl_add_u64 v[8:9], v[4:5], 0, v[8:9]
	global_load_ushort v35, v[8:9], off
	v_or_b32_e32 v8, 2, v2
	v_ashrrev_i32_e32 v9, 31, v8
	v_lshlrev_b64 v[8:9], 13, v[8:9]
	v_lshl_add_u64 v[8:9], v[4:5], 0, v[8:9]
	global_load_ushort v36, v[8:9], off
	v_or_b32_e32 v8, 3, v2
	v_ashrrev_i32_e32 v9, 31, v8
	v_lshlrev_b64 v[8:9], 13, v[8:9]
	v_lshl_add_u64 v[8:9], v[4:5], 0, v[8:9]
	global_load_ushort v37, v[8:9], off
	v_or_b32_e32 v8, 4, v2
	v_ashrrev_i32_e32 v9, 31, v8
	v_lshlrev_b64 v[8:9], 13, v[8:9]
	v_lshl_add_u64 v[8:9], v[4:5], 0, v[8:9]
	global_load_ushort v38, v[8:9], off
	v_or_b32_e32 v8, 5, v2
	v_ashrrev_i32_e32 v9, 31, v8
	v_lshlrev_b64 v[8:9], 13, v[8:9]
	v_lshl_add_u64 v[8:9], v[4:5], 0, v[8:9]
	global_load_ushort v39, v[8:9], off
	v_or_b32_e32 v8, 6, v2
	v_ashrrev_i32_e32 v9, 31, v8
	v_lshlrev_b64 v[8:9], 13, v[8:9]
	v_lshl_add_u64 v[8:9], v[4:5], 0, v[8:9]
	global_load_ushort v40, v[8:9], off
	v_or_b32_e32 v8, 7, v2
	v_ashrrev_i32_e32 v9, 31, v8
	v_lshlrev_b64 v[8:9], 13, v[8:9]
	v_lshl_add_u64 v[8:9], v[4:5], 0, v[8:9]
	global_load_ushort v41, v[8:9], off
	v_or_b32_e32 v8, 8, v2
	v_ashrrev_i32_e32 v9, 31, v8
	v_lshlrev_b64 v[8:9], 13, v[8:9]
	v_lshl_add_u64 v[8:9], v[4:5], 0, v[8:9]
	global_load_ushort v42, v[8:9], off
	v_or_b32_e32 v8, 9, v2
	v_ashrrev_i32_e32 v9, 31, v8
	v_lshlrev_b64 v[8:9], 13, v[8:9]
	v_lshl_add_u64 v[8:9], v[4:5], 0, v[8:9]
	global_load_ushort v43, v[8:9], off
	v_or_b32_e32 v8, 10, v2
	v_ashrrev_i32_e32 v9, 31, v8
	v_lshlrev_b64 v[8:9], 13, v[8:9]
	v_lshl_add_u64 v[8:9], v[4:5], 0, v[8:9]
	global_load_ushort v44, v[8:9], off
	v_or_b32_e32 v8, 11, v2
	v_ashrrev_i32_e32 v9, 31, v8
	v_lshlrev_b64 v[8:9], 13, v[8:9]
	v_lshl_add_u64 v[8:9], v[4:5], 0, v[8:9]
	global_load_ushort v45, v[8:9], off
	v_or_b32_e32 v8, 12, v2
	v_ashrrev_i32_e32 v9, 31, v8
	v_lshlrev_b64 v[8:9], 13, v[8:9]
	v_lshl_add_u64 v[8:9], v[4:5], 0, v[8:9]
	global_load_ushort v46, v[8:9], off
	v_or_b32_e32 v8, 13, v2
	v_ashrrev_i32_e32 v9, 31, v8
	v_lshlrev_b64 v[8:9], 13, v[8:9]
	v_lshl_add_u64 v[8:9], v[4:5], 0, v[8:9]
	global_load_ushort v47, v[8:9], off
	v_or_b32_e32 v8, 14, v2
	v_ashrrev_i32_e32 v9, 31, v8
	v_lshlrev_b64 v[8:9], 13, v[8:9]
	v_lshl_add_u64 v[8:9], v[4:5], 0, v[8:9]
	global_load_ushort v48, v[8:9], off
	v_or_b32_e32 v8, 15, v2
	v_ashrrev_i32_e32 v9, 31, v8
	v_lshlrev_b64 v[8:9], 13, v[8:9]
	v_lshl_add_u64 v[8:9], v[4:5], 0, v[8:9]
	global_load_ushort v49, v[8:9], off
	v_or_b32_e32 v8, 16, v2
	v_ashrrev_i32_e32 v9, 31, v8
	v_lshlrev_b64 v[8:9], 13, v[8:9]
	v_lshl_add_u64 v[8:9], v[4:5], 0, v[8:9]
	global_load_ushort v50, v[8:9], off
	v_or_b32_e32 v8, 17, v2
	v_ashrrev_i32_e32 v9, 31, v8
	v_lshlrev_b64 v[8:9], 13, v[8:9]
	v_lshl_add_u64 v[8:9], v[4:5], 0, v[8:9]
	global_load_ushort v51, v[8:9], off
	v_or_b32_e32 v8, 18, v2
	v_ashrrev_i32_e32 v9, 31, v8
	v_lshlrev_b64 v[8:9], 13, v[8:9]
	v_lshl_add_u64 v[8:9], v[4:5], 0, v[8:9]
	global_load_ushort v52, v[8:9], off
	v_or_b32_e32 v8, 19, v2
	v_ashrrev_i32_e32 v9, 31, v8
	v_lshlrev_b64 v[8:9], 13, v[8:9]
	v_lshl_add_u64 v[8:9], v[4:5], 0, v[8:9]
	global_load_ushort v53, v[8:9], off
	v_or_b32_e32 v8, 20, v2
	v_ashrrev_i32_e32 v9, 31, v8
	v_lshlrev_b64 v[8:9], 13, v[8:9]
	v_lshl_add_u64 v[8:9], v[4:5], 0, v[8:9]
	global_load_ushort v54, v[8:9], off
	v_or_b32_e32 v8, 21, v2
	v_ashrrev_i32_e32 v9, 31, v8
	v_lshlrev_b64 v[8:9], 13, v[8:9]
	v_lshl_add_u64 v[8:9], v[4:5], 0, v[8:9]
	global_load_ushort v55, v[8:9], off
	v_or_b32_e32 v8, 22, v2
	v_ashrrev_i32_e32 v9, 31, v8
	v_lshlrev_b64 v[8:9], 13, v[8:9]
	v_lshl_add_u64 v[8:9], v[4:5], 0, v[8:9]
	global_load_ushort v56, v[8:9], off
	v_or_b32_e32 v8, 23, v2
	v_ashrrev_i32_e32 v9, 31, v8
	v_lshlrev_b64 v[8:9], 13, v[8:9]
	v_lshl_add_u64 v[8:9], v[4:5], 0, v[8:9]
	global_load_ushort v57, v[8:9], off
	v_or_b32_e32 v8, 24, v2
	v_ashrrev_i32_e32 v9, 31, v8
	v_lshlrev_b64 v[8:9], 13, v[8:9]
	v_lshl_add_u64 v[8:9], v[4:5], 0, v[8:9]
	global_load_ushort v58, v[8:9], off
	v_or_b32_e32 v8, 25, v2
	v_ashrrev_i32_e32 v9, 31, v8
	v_lshlrev_b64 v[8:9], 13, v[8:9]
	v_lshl_add_u64 v[8:9], v[4:5], 0, v[8:9]
	global_load_ushort v59, v[8:9], off
	v_or_b32_e32 v8, 26, v2
	v_ashrrev_i32_e32 v9, 31, v8
	v_lshlrev_b64 v[8:9], 13, v[8:9]
	v_lshl_add_u64 v[8:9], v[4:5], 0, v[8:9]
	global_load_ushort v60, v[8:9], off
	v_or_b32_e32 v8, 27, v2
	v_ashrrev_i32_e32 v9, 31, v8
	v_lshlrev_b64 v[8:9], 13, v[8:9]
	v_lshl_add_u64 v[8:9], v[4:5], 0, v[8:9]
	global_load_ushort v61, v[8:9], off
	v_or_b32_e32 v8, 28, v2
	v_ashrrev_i32_e32 v9, 31, v8
	v_lshlrev_b64 v[8:9], 13, v[8:9]
	v_lshl_add_u64 v[8:9], v[4:5], 0, v[8:9]
	global_load_ushort v62, v[8:9], off
	v_or_b32_e32 v8, 29, v2
	v_ashrrev_i32_e32 v9, 31, v8
	v_lshlrev_b64 v[8:9], 13, v[8:9]
	v_lshl_add_u64 v[8:9], v[4:5], 0, v[8:9]
	global_load_ushort v63, v[8:9], off
	v_or_b32_e32 v8, 30, v2
	v_ashrrev_i32_e32 v9, 31, v8
	v_lshlrev_b64 v[8:9], 13, v[8:9]
	v_lshl_add_u64 v[8:9], v[4:5], 0, v[8:9]
	global_load_ushort v64, v[8:9], off
	v_or_b32_e32 v8, 31, v2
	v_ashrrev_i32_e32 v9, 31, v8
	v_lshlrev_b64 v[8:9], 13, v[8:9]
	v_lshl_add_u64 v[8:9], v[4:5], 0, v[8:9]
	global_load_ushort v65, v[8:9], off
	v_lshlrev_b32_e32 v1, 2, v1
	v_and_b32_e32 v3, 0x3fffffc0, v6
	v_lshlrev_b32_e32 v3, 2, v3
	v_add3_u32 v3, 0, v3, v1
	s_waitcnt vmcnt(0)
; __device__ __forceinline__ float bf2f(bf16_t h) { return __uint_as_float(((unsigned)h) << 16); }
; __device__ __forceinline__ int fresh_tid() { int t; asm volatile("v_mov_b32 %0, %1" : "=v"(t) : "v"(threadIdx.x)); return t; }
; __device__ __forceinline__ void kmean_items(const Ctx& a, LAS unsigned char* lds) {
;     ...
;         for (int i = 0; i < 32; ++i) s += bf2f(pa[(size_t)(n * 256 + tg * 32 + i) * PA + C_MK + hh * 64 + d]);
;         part[tg * 64 + d] = s;
;         __syncthreads();
;         if (fresh_tid() < 64) {
;             float tsum = 0.f;
; #pragma unroll
;             for (int g2 = 0; g2 < 8; ++g2) tsum += part[g2 * 64 + d];
;             kmean[(size_t)it * 64 + d] = tsum * (1.f / 256.f);
;         }
	v_lshlrev_b32_e32 v34, 16, v34
	v_add_f32_e32 v2, 0, v34
	v_lshlrev_b32_e32 v35, 16, v35
	v_add_f32_e32 v2, v2, v35
	v_lshlrev_b32_e32 v36, 16, v36
	v_add_f32_e32 v2, v2, v36
	v_lshlrev_b32_e32 v37, 16, v37
	v_add_f32_e32 v2, v2, v37
	v_lshlrev_b32_e32 v38, 16, v38
	v_add_f32_e32 v2, v2, v38
	v_lshlrev_b32_e32 v39, 16, v39
	v_add_f32_e32 v2, v2, v39
	v_lshlrev_b32_e32 v40, 16, v40
	v_add_f32_e32 v2, v2, v40
	v_lshlrev_b32_e32 v41, 16, v41
	v_add_f32_e32 v2, v2, v41
	v_lshlrev_b32_e32 v42, 16, v42
	v_add_f32_e32 v2, v2, v42
	v_lshlrev_b32_e32 v43, 16, v43
	v_add_f32_e32 v2, v2, v43
	v_lshlrev_b32_e32 v44, 16, v44
	v_add_f32_e32 v2, v2, v44
	v_lshlrev_b32_e32 v45, 16, v45
	v_add_f32_e32 v2, v2, v45
	v_lshlrev_b32_e32 v46, 16, v46
	v_add_f32_e32 v2, v2, v46
	v_lshlrev_b32_e32 v47, 16, v47
	v_add_f32_e32 v2, v2, v47
	v_lshlrev_b32_e32 v48, 16, v48
	v_add_f32_e32 v2, v2, v48
	v_lshlrev_b32_e32 v49, 16, v49
	v_add_f32_e32 v2, v2, v49
	v_lshlrev_b32_e32 v50, 16, v50
	v_add_f32_e32 v2, v2, v50
	v_lshlrev_b32_e32 v51, 16, v51
	v_add_f32_e32 v2, v2, v51
	v_lshlrev_b32_e32 v52, 16, v52
	v_add_f32_e32 v2, v2, v52
	v_lshlrev_b32_e32 v53, 16, v53
	v_add_f32_e32 v2, v2, v53
	v_lshlrev_b32_e32 v54, 16, v54
	v_add_f32_e32 v2, v2, v54
	v_lshlrev_b32_e32 v55, 16, v55
	v_add_f32_e32 v2, v2, v55
	v_lshlrev_b32_e32 v56, 16, v56
	v_add_f32_e32 v2, v2, v56
	v_lshlrev_b32_e32 v57, 16, v57
	v_add_f32_e32 v2, v2, v57
	v_lshlrev_b32_e32 v58, 16, v58
	v_add_f32_e32 v2, v2, v58
	v_lshlrev_b32_e32 v59, 16, v59
	v_add_f32_e32 v2, v2, v59
	v_lshlrev_b32_e32 v60, 16, v60
	v_add_f32_e32 v2, v2, v60
	v_lshlrev_b32_e32 v61, 16, v61
	v_add_f32_e32 v2, v2, v61
	v_lshlrev_b32_e32 v62, 16, v62
	v_add_f32_e32 v2, v2, v62
	v_lshlrev_b32_e32 v63, 16, v63
	v_add_f32_e32 v2, v2, v63
	v_lshlrev_b32_e32 v64, 16, v64
	v_add_f32_e32 v2, v2, v64
	v_lshlrev_b32_e32 v65, 16, v65
	v_add_f32_e32 v2, v2, v65
	ds_write_b32 v3, v2
	s_waitcnt lgkmcnt(0)
	s_barrier
	v_mov_b32 v2, v179
	s_nop 0
	v_cmp_gt_i32_e32 vcc, 64, v2
	s_and_saveexec_b64 s[12:13], vcc
	s_cbranch_execz .LBB0_331
	v_add_u32_e32 v4, 0, v1
	ds_read2st64_b32 v[2:3], v4 offset1:1
	s_ashr_i32 s1, s0, 31
	s_lshl_b64 s[36:37], s[0:1], 8
	v_readlane_b32 s6, v254, 38
	v_readlane_b32 s7, v254, 39
	s_waitcnt lgkmcnt(0)
	v_add_f32_e32 v2, 0, v2
	v_add_f32_e32 v5, v2, v3
	ds_read2st64_b32 v[2:3], v4 offset0:2 offset1:3
	s_add_u32 s36, s6, s36
	s_addc_u32 s37, s7, s37
	s_waitcnt lgkmcnt(0)
	v_add_f32_e32 v2, v5, v2
	v_add_f32_e32 v5, v2, v3
	ds_read2st64_b32 v[2:3], v4 offset0:4 offset1:5
	s_waitcnt lgkmcnt(0)
	v_add_f32_e32 v2, v5, v2
	v_add_f32_e32 v5, v2, v3
	ds_read2st64_b32 v[2:3], v4 offset0:6 offset1:7
	s_waitcnt lgkmcnt(0)
	v_add_f32_e32 v2, v5, v2
	v_add_f32_e32 v2, v2, v3
	v_mul_f32_e32 v2, 0x3b800000, v2
	global_store_dword v1, v2, s[36:37]
	s_branch .LBB0_331

; __device__ __forceinline__ TileIdx tile_idx() { TileIdx t; t.tid = fresh_tid(); t.wid = t.tid >> 6; t.lane = t.tid & 63; t.wr = t.wid >> 2; t.wc = t.wid & 3; t.fr = t.lane & 15; t.fq = t.lane >> 4; return t; }
; __device__ __forceinline__ float rstd_from_ssq(const float* ssq, int row) {
;     f32x4 s = *(const f32x4*)(ssq + (size_t)row * 4);
;     return rsqrtf((s[0] + s[1] + s[2] + s[3]) * (1.f / 1024.f) + EPS);
; }
; template <int MODE>
; __device__ __forceinline__ void epi_scaled(Acc& acc, int pm, int pn, const float* ssq, const float* rq, const float* rkv, bf16_t* out, int ldo) {
;     TileIdx t = tile_idx();
;     float rsv[2][4];
; #pragma unroll
;     for (int ai = 0; ai < 2; ++ai)
; #pragma unroll
;         for (int m = 0; m < 4; ++m) {
;             const int row = pm * 256 + ai * 128 + t.wr * 64 + m * 16 + t.fr;
;             if (MODE == 1) rsv[ai][m] = (pn < 3) ? rq[row] : rkv[row];
;             else rsv[ai][m] = rstd_from_ssq(ssq, row);
;         }
.LBB0_539:
	v_mov_b32 v1, v179
	s_nop 0
	v_ashrrev_i32_e32 v130, 2, v1
	v_and_b32_e32 v130, 0xffffffc0, v130
	v_and_or_b32 v131, v1, 15, s0
	v_add_u32_e32 v142, v131, v130
	v_add_u32_e32 v172, 0x0, v142
	v_ashrrev_i32_e32 v173, 31, v172
	v_lshl_add_u64 v[172:173], v[172:173], 4, s[14:15]
	global_load_dwordx4 v[174:177], v[172:173], off
	v_add_u32_e32 v172, 0x10, v142
	v_ashrrev_i32_e32 v173, 31, v172
	v_lshl_add_u64 v[172:173], v[172:173], 4, s[14:15]
	global_load_dwordx4 v[184:187], v[172:173], off
	v_add_u32_e32 v172, 0x30, v142
	v_ashrrev_i32_e32 v173, 31, v172
	v_lshl_add_u64 v[172:173], v[172:173], 4, s[14:15]
	global_load_dwordx4 v[188:191], v[172:173], off
	v_add_u32_e32 v172, 0x20, v142
	v_ashrrev_i32_e32 v173, 31, v172
	v_lshl_add_u64 v[172:173], v[172:173], 4, s[14:15]
	global_load_dwordx4 v[204:207], v[172:173], off
	v_add_u32_e32 v172, 0x90, v142
	v_ashrrev_i32_e32 v173, 31, v172
	v_lshl_add_u64 v[172:173], v[172:173], 4, s[14:15]
	global_load_dwordx4 v[208:211], v[172:173], off
	v_add_u32_e32 v172, 0x80, v142
	v_ashrrev_i32_e32 v173, 31, v172
	v_lshl_add_u64 v[172:173], v[172:173], 4, s[14:15]
	global_load_dwordx4 v[212:215], v[172:173], off
	v_add_u32_e32 v172, 0xb0, v142
	v_ashrrev_i32_e32 v173, 31, v172
	v_lshl_add_u64 v[172:173], v[172:173], 4, s[14:15]
	global_load_dwordx4 v[216:219], v[172:173], off
	v_add_u32_e32 v172, 0xa0, v142
	v_ashrrev_i32_e32 v173, 31, v172
	v_lshl_add_u64 v[172:173], v[172:173], 4, s[14:15]
	global_load_dwordx4 v[220:223], v[172:173], off
	s_waitcnt vmcnt(0)
	v_or_b32_e32 v140, 16, v142
	v_ashrrev_i32_e32 v143, 31, v142
	v_ashrrev_i32_e32 v141, 31, v140
	v_lshl_add_u64 v[130:131], v[142:143], 4, s[14:15]
	v_lshl_add_u64 v[134:135], v[140:141], 4, s[14:15]
	v_mov_b32_e32 v130, v174
	v_mov_b32_e32 v131, v175
	v_mov_b32_e32 v132, v176
	v_mov_b32_e32 v133, v177
	s_mov_b32 s0, 0x358637bd
	v_mov_b32_e32 v134, v184
	v_mov_b32_e32 v135, v185
	v_mov_b32_e32 v136, v186
	v_mov_b32_e32 v137, v187
	v_mov_b64_e32 v[156:157], s[0:1]
	v_or_b32_e32 v152, 32, v142
	v_or_b32_e32 v150, 48, v142
	v_ashrrev_i32_e32 v153, 31, v152
	v_ashrrev_i32_e32 v151, 31, v150
	v_add_u32_e32 v164, 0x80, v142
	v_add_u32_e32 v160, 0x90, v142
	v_ashrrev_i32_e32 v165, 31, v164
	v_ashrrev_i32_e32 v161, 31, v160
	v_add_u32_e32 v168, 0xa0, v142
	v_add_u32_e32 v166, 0xb0, v142
	v_ashrrev_i32_e32 v169, 31, v168
	v_ashrrev_i32_e32 v167, 31, v166
	v_and_b32_e32 v144, 0xc0, v1
	s_waitcnt vmcnt(0)
	v_mov_b32_e32 v139, v130
	v_mov_b32_e32 v138, v134
	v_mov_b32_e32 v130, v135
	v_pk_add_f32 v[130:131], v[138:139], v[130:131]
	v_mov_b32_e32 v134, v136
	v_mov_b32_e32 v135, v132
	v_pk_add_f32 v[130:131], v[134:135], v[130:131]
	v_mov_b32_e32 v132, v137
	v_pk_add_f32 v[130:131], v[132:133], v[130:131]
	v_lshl_add_u64 v[134:135], v[150:151], 4, s[14:15]
	v_pk_fma_f32 v[130:131], v[130:131], s[28:29], v[156:157] op_sel_hi:[1,0,0]
	v_mov_b32_e32 v134, v188
	v_mov_b32_e32 v135, v189
	v_mov_b32_e32 v136, v190
	v_mov_b32_e32 v137, v191
	v_mul_f32_e32 v132, 0x4b800000, v131
	v_cmp_gt_f32_e64 s[0:1], s88, v131
	v_cmp_gt_f32_e32 vcc, s88, v130
	s_waitcnt vmcnt(0)
	v_mov_b32_e32 v148, v134
	v_cndmask_b32_e64 v131, v131, v132, s[0:1]
	v_rsq_f32_e32 v131, v131
	v_mov_b32_e32 v134, v136
	v_mul_f32_e32 v132, 0x45800000, v131
	v_cndmask_b32_e64 v146, v131, v132, s[0:1]
	v_mul_f32_e32 v131, 0x4b800000, v130
	v_cndmask_b32_e32 v130, v130, v131, vcc
	v_rsq_f32_e32 v130, v130
	v_pk_mul_f32 v[116:117], v[116:117], v[146:147] op_sel_hi:[1,0]
	v_pk_mul_f32 v[114:115], v[114:115], v[146:147] op_sel_hi:[1,0]
	v_pk_mul_f32 v[120:121], v[120:121], v[146:147] op_sel_hi:[1,0]
	v_mul_f32_e32 v131, 0x45800000, v130
	v_cndmask_b32_e32 v138, v130, v131, vcc
	v_lshl_add_u64 v[130:131], v[152:153], 4, s[14:15]
	v_mov_b32_e32 v130, v204
	v_mov_b32_e32 v131, v205
	v_mov_b32_e32 v132, v206
	v_mov_b32_e32 v133, v207
	v_cvt_pk_bf16_f32 v114, v114, v115
	v_cvt_pk_bf16_f32 v115, v116, v117
	v_pk_mul_f32 v[116:117], v[126:127], v[146:147] op_sel_hi:[1,0]
	v_pk_mul_f32 v[100:101], v[100:101], v[138:139] op_sel_hi:[1,0]
	v_cvt_pk_bf16_f32 v116, v116, v117
	v_pk_mul_f32 v[98:99], v[98:99], v[138:139] op_sel_hi:[1,0]
	v_pk_mul_f32 v[118:119], v[118:119], v[146:147] op_sel_hi:[1,0]
	v_cvt_pk_bf16_f32 v98, v98, v99
	v_cvt_pk_bf16_f32 v99, v100, v101
	v_pk_mul_f32 v[100:101], v[110:111], v[138:139] op_sel_hi:[1,0]
	v_pk_mul_f32 v[104:105], v[104:105], v[138:139] op_sel_hi:[1,0]
	v_cvt_pk_bf16_f32 v100, v100, v101
	v_pk_mul_f32 v[102:103], v[102:103], v[138:139] op_sel_hi:[1,0]
	v_cvt_pk_bf16_f32 v118, v118, v119
	v_cvt_pk_bf16_f32 v119, v120, v121
	v_cvt_pk_bf16_f32 v102, v102, v103
	v_cvt_pk_bf16_f32 v103, v104, v105
	s_waitcnt vmcnt(0)
	v_mov_b32_e32 v149, v130
	v_mov_b32_e32 v130, v135
	v_pk_add_f32 v[130:131], v[148:149], v[130:131]
	v_mov_b32_e32 v135, v132
	v_pk_add_f32 v[130:131], v[134:135], v[130:131]
	v_mov_b32_e32 v132, v137
	v_pk_add_f32 v[130:131], v[132:133], v[130:131]
	v_lshl_add_u64 v[134:135], v[160:161], 4, s[14:15]
	v_pk_fma_f32 v[130:131], v[130:131], s[28:29], v[156:157] op_sel_hi:[1,0,0]
	v_mov_b32_e32 v134, v208
	v_mov_b32_e32 v135, v209
	v_mov_b32_e32 v136, v210
	v_mov_b32_e32 v137, v211
	v_mul_f32_e32 v132, 0x4b800000, v131
	v_cmp_gt_f32_e64 s[0:1], s88, v131
	v_cmp_gt_f32_e32 vcc, s88, v130
	s_waitcnt vmcnt(0)
; __device__ __forceinline__ unsigned cvt_pk(float lo, float hi) { f32x2_t v = {lo, hi}; bf16x2_t b = __builtin_convertvector(v, bf16x2_t); return __builtin_bit_cast(unsigned, b); }
; __device__ __forceinline__ float sigmoidf_(float x) { return __builtin_amdgcn_rcpf(1.f + __builtin_amdgcn_exp2f(-1.4426950408889634f * x)); }
; template <int MODE>
; __device__ __forceinline__ void epi_scaled(Acc& acc, int pm, int pn, const float* ssq, const float* rq, const float* rkv, bf16_t* out, int ldo) {
;     ...
; #pragma unroll
;     for (int ai = 0; ai < 2; ++ai)
; #pragma unroll
;         for (int m = 0; m < 4; ++m) {
;             int row = pm * 256 + ai * 128 + t.wr * 64 + m * 16 + t.fr;
;             const float rs = rsv[ai][m];
; #pragma unroll
;             for (int bj = 0; bj < 2; ++bj)
; #pragma unroll
;                 for (int n = 0; n < 2; ++n) {
;                     f32x4 v = acc[ai][bj][m][n] * rs;
;                     if (MODE == 2) {
; #pragma unroll
;                         for (int j = 0; j < 4; ++j) v[j] = sigmoidf_(v[j]);
;                     }
;                     u32x2 w; w[0] = cvt_pk(v[0], v[1]); w[1] = cvt_pk(v[2], v[3]);
;                     *(u32x2*)(out + (size_t)row * ldo + pn * 256 + bj * 128 + t.wc * 32 + n * 16 + t.fq * 4) = w;
;                 }
;         }
	v_mov_b32_e32 v158, v134
	v_cndmask_b32_e64 v131, v131, v132, s[0:1]
	v_rsq_f32_e32 v131, v131
	v_mov_b32_e32 v134, v136
	v_mul_f32_e32 v132, 0x45800000, v131
	v_cndmask_b32_e64 v154, v131, v132, s[0:1]
	v_mul_f32_e32 v131, 0x4b800000, v130
	v_cndmask_b32_e32 v130, v130, v131, vcc
	v_rsq_f32_e32 v130, v130
	v_pk_mul_f32 v[84:85], v[84:85], v[154:155] op_sel_hi:[1,0]
	v_pk_mul_f32 v[82:83], v[82:83], v[154:155] op_sel_hi:[1,0]
	v_pk_mul_f32 v[88:89], v[88:89], v[154:155] op_sel_hi:[1,0]
	v_mul_f32_e32 v131, 0x45800000, v130
	v_cndmask_b32_e32 v148, v130, v131, vcc
	v_lshl_add_u64 v[130:131], v[164:165], 4, s[14:15]
	v_mov_b32_e32 v130, v212
	v_mov_b32_e32 v131, v213
	v_mov_b32_e32 v132, v214
	v_mov_b32_e32 v133, v215
	v_cvt_pk_bf16_f32 v82, v82, v83
	v_cvt_pk_bf16_f32 v83, v84, v85
	v_pk_mul_f32 v[84:85], v[94:95], v[154:155] op_sel_hi:[1,0]
	v_pk_mul_f32 v[52:53], v[52:53], v[148:149] op_sel_hi:[1,0]
	v_cvt_pk_bf16_f32 v84, v84, v85
	v_pk_mul_f32 v[50:51], v[50:51], v[148:149] op_sel_hi:[1,0]
	v_pk_mul_f32 v[64:65], v[64:65], v[148:149] op_sel_hi:[1,0]
	v_cvt_pk_bf16_f32 v50, v50, v51
	v_cvt_pk_bf16_f32 v51, v52, v53
	v_pk_mul_f32 v[52:53], v[78:79], v[148:149] op_sel_hi:[1,0]
	v_pk_mul_f32 v[62:63], v[62:63], v[148:149] op_sel_hi:[1,0]
	v_cvt_pk_bf16_f32 v52, v52, v53
	v_cvt_pk_bf16_f32 v62, v62, v63
	v_cvt_pk_bf16_f32 v63, v64, v65
	v_pk_mul_f32 v[86:87], v[86:87], v[154:155] op_sel_hi:[1,0]
	s_waitcnt vmcnt(0)
	v_mov_b32_e32 v159, v130
	v_mov_b32_e32 v130, v135
	v_pk_add_f32 v[130:131], v[158:159], v[130:131]
	v_mov_b32_e32 v135, v132
	v_pk_add_f32 v[130:131], v[134:135], v[130:131]
	v_mov_b32_e32 v132, v137
	v_pk_add_f32 v[130:131], v[132:133], v[130:131]
	v_lshl_add_u64 v[134:135], v[166:167], 4, s[14:15]
	v_pk_fma_f32 v[130:131], v[130:131], s[28:29], v[156:157] op_sel_hi:[1,0,0]
	v_mov_b32_e32 v134, v216
	v_mov_b32_e32 v135, v217
	v_mov_b32_e32 v136, v218
	v_mov_b32_e32 v137, v219
	v_mul_f32_e32 v132, 0x4b800000, v131
	v_cmp_gt_f32_e64 s[0:1], s88, v131
	v_cmp_gt_f32_e32 vcc, s88, v130
	v_cvt_pk_bf16_f32 v86, v86, v87
	v_cndmask_b32_e64 v131, v131, v132, s[0:1]
	v_rsq_f32_e32 v131, v131
	v_cvt_pk_bf16_f32 v87, v88, v89
	v_mul_f32_e32 v132, 0x45800000, v131
	v_cndmask_b32_e64 v162, v131, v132, s[0:1]
	v_mul_f32_e32 v131, 0x4b800000, v130
	v_cndmask_b32_e32 v130, v130, v131, vcc
	v_rsq_f32_e32 v130, v130
	v_pk_mul_f32 v[54:55], v[54:55], v[162:163] op_sel_hi:[1,0]
	v_mul_f32_e32 v131, 0x45800000, v130
	v_cndmask_b32_e32 v158, v130, v131, vcc
	v_lshl_add_u64 v[130:131], v[168:169], 4, s[14:15]
	v_mov_b32_e32 v130, v220
	v_mov_b32_e32 v131, v221
	v_mov_b32_e32 v132, v222
	v_mov_b32_e32 v133, v223
	v_cvt_pk_bf16_f32 v54, v54, v55
	v_pk_mul_f32 v[36:37], v[36:37], v[158:159] op_sel_hi:[1,0]
	v_pk_mul_f32 v[34:35], v[34:35], v[158:159] op_sel_hi:[1,0]
	v_pk_mul_f32 v[44:45], v[44:45], v[158:159] op_sel_hi:[1,0]
	v_cvt_pk_bf16_f32 v34, v34, v35
	v_cvt_pk_bf16_f32 v35, v36, v37
	v_pk_mul_f32 v[36:37], v[46:47], v[158:159] op_sel_hi:[1,0]
	v_pk_mul_f32 v[42:43], v[42:43], v[158:159] op_sel_hi:[1,0]
	v_cvt_pk_bf16_f32 v36, v36, v37
	v_cvt_pk_bf16_f32 v42, v42, v43
	v_cvt_pk_bf16_f32 v43, v44, v45
	s_waitcnt vmcnt(0)
	v_mov_b32_e32 v170, v134
	v_mov_b32_e32 v134, v136
	v_mov_b32_e32 v171, v130
	v_mov_b32_e32 v130, v135
	v_pk_add_f32 v[130:131], v[170:171], v[130:131]
	v_mov_b32_e32 v135, v132
	v_pk_add_f32 v[130:131], v[134:135], v[130:131]
	v_mov_b32_e32 v132, v137
	v_pk_add_f32 v[130:131], v[132:133], v[130:131]
	v_lshlrev_b64 v[136:137], 13, v[142:143]
	v_pk_fma_f32 v[130:131], v[130:131], s[28:29], v[156:157] op_sel_hi:[1,0,0]
	s_nop 0
	v_mul_f32_e32 v132, 0x4b800000, v131
	v_cmp_gt_f32_e64 s[0:1], s88, v131
	v_cmp_gt_f32_e32 vcc, s88, v130
	s_nop 0
	v_cndmask_b32_e64 v131, v131, v132, s[0:1]
	v_rsq_f32_e32 v131, v131
	s_nop 0
	v_mul_f32_e32 v132, 0x45800000, v131
	v_cndmask_b32_e64 v132, v131, v132, s[0:1]
	v_mul_f32_e32 v131, 0x4b800000, v130
	v_cndmask_b32_e32 v130, v130, v131, vcc
	v_rsq_f32_e32 v130, v130
	s_lshl_b64 s[0:1], s[12:13], 1
	s_add_u32 s0, s70, s0
	s_addc_u32 s1, s71, s1
	v_mul_f32_e32 v131, 0x45800000, v130
	v_cndmask_b32_e32 v130, v130, v131, vcc
	v_lshrrev_b32_e32 v131, 1, v1
	v_lshl_add_u64 v[134:135], s[0:1], 0, v[144:145]
	v_and_b32_e32 v144, 24, v131
	v_lshl_add_u64 v[134:135], v[134:135], 0, v[144:145]
	v_lshl_add_u64 v[136:137], v[134:135], 0, v[136:137]
	global_store_dwordx2 v[136:137], v[114:115], off offset:32
	v_pk_mul_f32 v[114:115], v[128:129], v[146:147] op_sel_hi:[1,0]
	v_pk_mul_f32 v[20:21], v[20:21], v[132:133] op_sel_hi:[1,0]
	v_cvt_pk_bf16_f32 v117, v114, v115
	global_store_dwordx2 v[136:137], v[116:117], off offset:256
	v_pk_mul_f32 v[114:115], v[124:125], v[146:147] op_sel_hi:[1,0]
	v_pk_mul_f32 v[116:117], v[122:123], v[146:147] op_sel_hi:[1,0]
	v_pk_mul_f32 v[18:19], v[18:19], v[132:133] op_sel_hi:[1,0]
	v_cvt_pk_bf16_f32 v116, v116, v117
	v_cvt_pk_bf16_f32 v117, v114, v115
	v_lshlrev_b64 v[114:115], 13, v[140:141]
	v_lshl_add_u64 v[114:115], v[134:135], 0, v[114:115]
	global_store_dwordx2 v[114:115], v[98:99], off offset:32
	v_pk_mul_f32 v[98:99], v[112:113], v[138:139] op_sel_hi:[1,0]
	v_cvt_pk_bf16_f32 v18, v18, v19
	v_cvt_pk_bf16_f32 v101, v98, v99
; __device__ __forceinline__ unsigned cvt_pk(float lo, float hi) { f32x2_t v = {lo, hi}; bf16x2_t b = __builtin_convertvector(v, bf16x2_t); return __builtin_bit_cast(unsigned, b); }
; __device__ __forceinline__ float sigmoidf_(float x) { return __builtin_amdgcn_rcpf(1.f + __builtin_amdgcn_exp2f(-1.4426950408889634f * x)); }
; template <int MODE>
; __device__ __forceinline__ void epi_scaled(Acc& acc, int pm, int pn, const float* ssq, const float* rq, const float* rkv, bf16_t* out, int ldo) {
;     ...
;             for (int bj = 0; bj < 2; ++bj)
; #pragma unroll
;                 for (int n = 0; n < 2; ++n) {
;                     f32x4 v = acc[ai][bj][m][n] * rs;
;                     if (MODE == 2) {
; #pragma unroll
;                         for (int j = 0; j < 4; ++j) v[j] = sigmoidf_(v[j]);
;                     }
;                     u32x2 w; w[0] = cvt_pk(v[0], v[1]); w[1] = cvt_pk(v[2], v[3]);
;                     *(u32x2*)(out + (size_t)row * ldo + pn * 256 + bj * 128 + t.wc * 32 + n * 16 + t.fq * 4) = w;
;                 }
; __device__ __forceinline__ void phase_proj(const Ctx& a, int b, LAS unsigned char* lds) {
;     ...
;         __syncthreads();
	global_store_dwordx2 v[114:115], v[100:101], off offset:256
	v_pk_mul_f32 v[98:99], v[108:109], v[138:139] op_sel_hi:[1,0]
	v_pk_mul_f32 v[100:101], v[106:107], v[138:139] op_sel_hi:[1,0]
	v_cvt_pk_bf16_f32 v19, v20, v21
	v_cvt_pk_bf16_f32 v100, v100, v101
	v_cvt_pk_bf16_f32 v101, v98, v99
	v_lshlrev_b64 v[98:99], 13, v[152:153]
	v_lshl_add_u64 v[98:99], v[134:135], 0, v[98:99]
	global_store_dwordx2 v[98:99], v[82:83], off offset:32
	v_pk_mul_f32 v[82:83], v[96:97], v[154:155] op_sel_hi:[1,0]
	v_pk_mul_f32 v[20:21], v[30:31], v[132:133] op_sel_hi:[1,0]
	v_cvt_pk_bf16_f32 v85, v82, v83
	global_store_dwordx2 v[98:99], v[84:85], off offset:256
	v_pk_mul_f32 v[82:83], v[92:93], v[154:155] op_sel_hi:[1,0]
	v_pk_mul_f32 v[84:85], v[90:91], v[154:155] op_sel_hi:[1,0]
	v_cvt_pk_bf16_f32 v20, v20, v21
	v_cvt_pk_bf16_f32 v84, v84, v85
	v_cvt_pk_bf16_f32 v85, v82, v83
	v_lshlrev_b64 v[82:83], 13, v[150:151]
	v_lshl_add_u64 v[82:83], v[134:135], 0, v[82:83]
	global_store_dwordx2 v[82:83], v[50:51], off offset:32
	v_pk_mul_f32 v[50:51], v[80:81], v[148:149] op_sel_hi:[1,0]
	global_store_dwordx2 v[82:83], v[62:63], off
	v_cvt_pk_bf16_f32 v53, v50, v51
	global_store_dwordx2 v[82:83], v[52:53], off offset:256
	v_pk_mul_f32 v[50:51], v[68:69], v[148:149] op_sel_hi:[1,0]
	v_pk_mul_f32 v[52:53], v[66:67], v[148:149] op_sel_hi:[1,0]
	v_pk_mul_f32 v[62:63], v[70:71], v[162:163] op_sel_hi:[1,0]
	v_cvt_pk_bf16_f32 v52, v52, v53
	v_cvt_pk_bf16_f32 v53, v50, v51
	global_store_dwordx2 v[82:83], v[52:53], off offset:288
	v_pk_mul_f32 v[52:53], v[72:73], v[162:163] op_sel_hi:[1,0]
	v_lshlrev_b64 v[50:51], 13, v[164:165]
	v_cvt_pk_bf16_f32 v62, v62, v63
	v_cvt_pk_bf16_f32 v63, v52, v53
	v_pk_mul_f32 v[52:53], v[56:57], v[162:163] op_sel_hi:[1,0]
	v_lshl_add_u64 v[50:51], v[134:135], 0, v[50:51]
	v_cvt_pk_bf16_f32 v55, v52, v53
	global_store_dwordx2 v[50:51], v[54:55], off offset:32
	v_pk_mul_f32 v[52:53], v[76:77], v[162:163] op_sel_hi:[1,0]
	v_pk_mul_f32 v[54:55], v[74:75], v[162:163] op_sel_hi:[1,0]
	global_store_dwordx2 v[50:51], v[62:63], off
	v_cvt_pk_bf16_f32 v54, v54, v55
	v_cvt_pk_bf16_f32 v55, v52, v53
	global_store_dwordx2 v[50:51], v[54:55], off offset:256
	v_pk_mul_f32 v[52:53], v[60:61], v[162:163] op_sel_hi:[1,0]
	v_pk_mul_f32 v[54:55], v[58:59], v[162:163] op_sel_hi:[1,0]
	v_pk_mul_f32 v[4:5], v[4:5], v[130:131] op_sel_hi:[1,0]
	v_cvt_pk_bf16_f32 v54, v54, v55
	v_cvt_pk_bf16_f32 v55, v52, v53
	global_store_dwordx2 v[50:51], v[54:55], off offset:288
	v_lshlrev_b64 v[50:51], 13, v[160:161]
	v_lshl_add_u64 v[50:51], v[134:135], 0, v[50:51]
	global_store_dwordx2 v[50:51], v[34:35], off offset:32
	v_pk_mul_f32 v[34:35], v[48:49], v[158:159] op_sel_hi:[1,0]
	v_pk_mul_f32 v[2:3], v[2:3], v[130:131] op_sel_hi:[1,0]
	v_cvt_pk_bf16_f32 v37, v34, v35
	global_store_dwordx2 v[50:51], v[36:37], off offset:256
	v_pk_mul_f32 v[34:35], v[40:41], v[158:159] op_sel_hi:[1,0]
	v_pk_mul_f32 v[36:37], v[38:39], v[158:159] op_sel_hi:[1,0]
	v_cvt_pk_bf16_f32 v2, v2, v3
	v_cvt_pk_bf16_f32 v36, v36, v37
	v_cvt_pk_bf16_f32 v37, v34, v35
	v_lshlrev_b64 v[34:35], 13, v[168:169]
	v_lshl_add_u64 v[34:35], v[134:135], 0, v[34:35]
	global_store_dwordx2 v[34:35], v[18:19], off offset:32
	v_pk_mul_f32 v[18:19], v[32:33], v[132:133] op_sel_hi:[1,0]
	v_cvt_pk_bf16_f32 v3, v4, v5
	v_cvt_pk_bf16_f32 v21, v18, v19
	global_store_dwordx2 v[34:35], v[20:21], off offset:256
	v_pk_mul_f32 v[18:19], v[24:25], v[132:133] op_sel_hi:[1,0]
	v_pk_mul_f32 v[20:21], v[22:23], v[132:133] op_sel_hi:[1,0]
	v_pk_mul_f32 v[4:5], v[14:15], v[130:131] op_sel_hi:[1,0]
	v_cvt_pk_bf16_f32 v20, v20, v21
	v_cvt_pk_bf16_f32 v21, v18, v19
	v_lshlrev_b64 v[18:19], 13, v[166:167]
	v_lshl_add_u64 v[18:19], v[134:135], 0, v[18:19]
	global_store_dwordx2 v[18:19], v[2:3], off offset:32
	v_pk_mul_f32 v[2:3], v[16:17], v[130:131] op_sel_hi:[1,0]
	v_cvt_pk_bf16_f32 v4, v4, v5
	v_cvt_pk_bf16_f32 v5, v2, v3
	v_pk_mul_f32 v[28:29], v[28:29], v[132:133] op_sel_hi:[1,0]
	v_pk_mul_f32 v[26:27], v[26:27], v[132:133] op_sel_hi:[1,0]
	v_pk_mul_f32 v[12:13], v[12:13], v[130:131] op_sel_hi:[1,0]
	v_pk_mul_f32 v[10:11], v[10:11], v[130:131] op_sel_hi:[1,0]
	global_store_dwordx2 v[18:19], v[4:5], off offset:256
	v_pk_mul_f32 v[2:3], v[8:9], v[130:131] op_sel_hi:[1,0]
	v_pk_mul_f32 v[4:5], v[6:7], v[130:131] op_sel_hi:[1,0]
	v_cvt_pk_bf16_f32 v26, v26, v27
	v_cvt_pk_bf16_f32 v27, v28, v29
	v_cvt_pk_bf16_f32 v10, v10, v11
	v_cvt_pk_bf16_f32 v11, v12, v13
	v_cvt_pk_bf16_f32 v4, v4, v5
	v_cvt_pk_bf16_f32 v5, v2, v3
	s_and_b64 vcc, exec, s[36:37]
	global_store_dwordx2 v[136:137], v[118:119], off
	global_store_dwordx2 v[136:137], v[116:117], off offset:288
	global_store_dwordx2 v[114:115], v[102:103], off
	global_store_dwordx2 v[114:115], v[100:101], off offset:288
	global_store_dwordx2 v[98:99], v[86:87], off
	global_store_dwordx2 v[98:99], v[84:85], off offset:288
	global_store_dwordx2 v[50:51], v[42:43], off
	global_store_dwordx2 v[50:51], v[36:37], off offset:288
	global_store_dwordx2 v[34:35], v[26:27], off
	global_store_dwordx2 v[34:35], v[20:21], off offset:288
	global_store_dwordx2 v[18:19], v[10:11], off
	global_store_dwordx2 v[18:19], v[4:5], off offset:288
	s_waitcnt lgkmcnt(0)
	s_barrier
	s_cbranch_vccnz .LBB0_535

; __device__ __forceinline__ TileIdx tile_idx() { TileIdx t; t.tid = fresh_tid(); t.wid = t.tid >> 6; t.lane = t.tid & 63; t.wr = t.wid >> 2; t.wc = t.wid & 3; t.fr = t.lane & 15; t.fq = t.lane >> 4; return t; }
; __device__ __forceinline__ float rstd_from_ssq(const float* ssq, int row) {
;     f32x4 s = *(const f32x4*)(ssq + (size_t)row * 4);
;     return rsqrtf((s[0] + s[1] + s[2] + s[3]) * (1.f / 1024.f) + EPS);
; }
; template <int MODE>
; __device__ __forceinline__ void epi_scaled(Acc& acc, int pm, int pn, const float* ssq, const float* rq, const float* rkv, bf16_t* out, int ldo) {
;     TileIdx t = tile_idx();
;     float rsv[2][4];
; #pragma unroll
;     for (int ai = 0; ai < 2; ++ai)
; #pragma unroll
;         for (int m = 0; m < 4; ++m) {
;             const int row = pm * 256 + ai * 128 + t.wr * 64 + m * 16 + t.fr;
;             if (MODE == 1) rsv[ai][m] = (pn < 3) ? rq[row] : rkv[row];
;             else rsv[ai][m] = rstd_from_ssq(ssq, row);
;         }
.LBB0_744:
	v_mov_b32 v1, v179
	s_nop 0
	v_ashrrev_i32_e32 v130, 2, v1
	v_and_b32_e32 v130, 0xffffffc0, v130
	v_and_or_b32 v131, v1, 15, s0
	v_add_u32_e32 v166, v131, v130
	v_add_u32_e32 v172, 0x0, v166
	v_ashrrev_i32_e32 v173, 31, v172
	v_lshl_add_u64 v[172:173], v[172:173], 4, s[22:23]
	global_load_dwordx4 v[174:177], v[172:173], off
	v_add_u32_e32 v172, 0x10, v166
	v_ashrrev_i32_e32 v173, 31, v172
	v_lshl_add_u64 v[172:173], v[172:173], 4, s[22:23]
	global_load_dwordx4 v[184:187], v[172:173], off
	v_add_u32_e32 v172, 0x30, v166
	v_ashrrev_i32_e32 v173, 31, v172
	v_lshl_add_u64 v[172:173], v[172:173], 4, s[22:23]
	global_load_dwordx4 v[188:191], v[172:173], off
	v_add_u32_e32 v172, 0x20, v166
	v_ashrrev_i32_e32 v173, 31, v172
	v_lshl_add_u64 v[172:173], v[172:173], 4, s[22:23]
	global_load_dwordx4 v[200:203], v[172:173], off
	v_add_u32_e32 v172, 0x90, v166
	v_ashrrev_i32_e32 v173, 31, v172
	v_lshl_add_u64 v[172:173], v[172:173], 4, s[22:23]
	global_load_dwordx4 v[204:207], v[172:173], off
	v_add_u32_e32 v172, 0x80, v166
	v_ashrrev_i32_e32 v173, 31, v172
	v_lshl_add_u64 v[172:173], v[172:173], 4, s[22:23]
	global_load_dwordx4 v[208:211], v[172:173], off
	v_add_u32_e32 v172, 0xb0, v166
	v_ashrrev_i32_e32 v173, 31, v172
	v_lshl_add_u64 v[172:173], v[172:173], 4, s[22:23]
	global_load_dwordx4 v[212:215], v[172:173], off
	v_add_u32_e32 v172, 0xa0, v166
	v_ashrrev_i32_e32 v173, 31, v172
	v_lshl_add_u64 v[172:173], v[172:173], 4, s[22:23]
	global_load_dwordx4 v[216:219], v[172:173], off
	s_waitcnt vmcnt(0)
	v_or_b32_e32 v162, 16, v166
	v_ashrrev_i32_e32 v167, 31, v166
	v_ashrrev_i32_e32 v163, 31, v162
	v_lshl_add_u64 v[130:131], v[166:167], 4, s[22:23]
	v_lshl_add_u64 v[134:135], v[162:163], 4, s[22:23]
	v_mov_b32_e32 v130, v174
	v_mov_b32_e32 v131, v175
	v_mov_b32_e32 v132, v176
	v_mov_b32_e32 v133, v177
	s_mov_b32 s0, 0x358637bd
	v_mov_b32_e32 v134, v184
	v_mov_b32_e32 v135, v185
	v_mov_b32_e32 v136, v186
	v_mov_b32_e32 v137, v187
	v_mov_b64_e32 v[168:169], s[0:1]
	v_or_b32_e32 v160, 32, v166
	v_or_b32_e32 v154, 48, v166
	v_ashrrev_i32_e32 v161, 31, v160
	v_ashrrev_i32_e32 v155, 31, v154
	v_add_u32_e32 v152, 0x80, v166
	v_add_u32_e32 v146, 0x90, v166
	v_ashrrev_i32_e32 v153, 31, v152
	v_ashrrev_i32_e32 v147, 31, v146
	v_add_u32_e32 v142, 0xa0, v166
	v_ashrrev_i32_e32 v143, 31, v142
	v_and_b32_e32 v144, 0xc0, v1
	s_waitcnt vmcnt(0)
	v_mov_b32_e32 v139, v130
	v_mov_b32_e32 v138, v134
	v_mov_b32_e32 v130, v135
	v_pk_add_f32 v[130:131], v[138:139], v[130:131]
	v_mov_b32_e32 v134, v136
	v_mov_b32_e32 v135, v132
	v_pk_add_f32 v[130:131], v[134:135], v[130:131]
	v_mov_b32_e32 v132, v137
	v_pk_add_f32 v[130:131], v[132:133], v[130:131]
	v_lshl_add_u64 v[134:135], v[154:155], 4, s[22:23]
	v_pk_fma_f32 v[130:131], v[130:131], s[28:29], v[168:169] op_sel_hi:[1,0,0]
	v_mov_b32_e32 v134, v188
	v_mov_b32_e32 v135, v189
	v_mov_b32_e32 v136, v190
	v_mov_b32_e32 v137, v191
	v_mul_f32_e32 v132, 0x4b800000, v131
	v_cmp_gt_f32_e64 s[0:1], s88, v131
	v_cmp_gt_f32_e32 vcc, s88, v130
	s_waitcnt vmcnt(0)
	v_mov_b32_e32 v138, v134
	v_cndmask_b32_e64 v131, v131, v132, s[0:1]
	v_rsq_f32_e32 v131, v131
	v_mov_b32_e32 v134, v136
	v_mul_f32_e32 v132, 0x45800000, v131
	v_cndmask_b32_e64 v164, v131, v132, s[0:1]
	v_mul_f32_e32 v131, 0x4b800000, v130
	v_cndmask_b32_e32 v130, v130, v131, vcc
	v_rsq_f32_e32 v130, v130
	v_pk_mul_f32 v[126:127], v[126:127], v[164:165] op_sel_hi:[1,0]
	v_pk_mul_f32 v[122:123], v[122:123], v[164:165] op_sel_hi:[1,0]
	v_pk_mul_f32 v[118:119], v[118:119], v[164:165] op_sel_hi:[1,0]
	v_mul_f32_e32 v131, 0x45800000, v130
	v_cndmask_b32_e32 v158, v130, v131, vcc
	v_lshl_add_u64 v[130:131], v[160:161], 4, s[22:23]
	v_mov_b32_e32 v130, v200
	v_mov_b32_e32 v131, v201
	v_mov_b32_e32 v132, v202
	v_mov_b32_e32 v133, v203
	v_pk_mul_f32 v[114:115], v[114:115], v[164:165] op_sel_hi:[1,0]
	v_pk_mul_f32 v[110:111], v[110:111], v[158:159] op_sel_hi:[1,0]
	v_pk_mul_f32 v[106:107], v[106:107], v[158:159] op_sel_hi:[1,0]
	v_pk_mul_f32 v[102:103], v[102:103], v[158:159] op_sel_hi:[1,0]
	v_pk_mul_f32 v[98:99], v[98:99], v[158:159] op_sel_hi:[1,0]
	v_pk_mul_f32 v[116:117], v[116:117], v[164:165] op_sel_hi:[1,0]
	v_pk_mul_f32 v[100:101], v[100:101], v[158:159] op_sel_hi:[1,0]
	v_pk_mul_f32 v[128:129], v[128:129], v[164:165] op_sel_hi:[1,0]
	v_pk_mul_f32 v[124:125], v[124:125], v[164:165] op_sel_hi:[1,0]
	v_pk_mul_f32 v[120:121], v[120:121], v[164:165] op_sel_hi:[1,0]
	v_pk_mul_f32 v[112:113], v[112:113], v[158:159] op_sel_hi:[1,0]
	v_pk_mul_f32 v[108:109], v[108:109], v[158:159] op_sel_hi:[1,0]
	v_pk_mul_f32 v[104:105], v[104:105], v[158:159] op_sel_hi:[1,0]
	s_waitcnt vmcnt(0)
	v_mov_b32_e32 v139, v130
	v_mov_b32_e32 v130, v135
	v_pk_add_f32 v[130:131], v[138:139], v[130:131]
	v_mov_b32_e32 v135, v132
	v_pk_add_f32 v[130:131], v[134:135], v[130:131]
	v_mov_b32_e32 v132, v137
	v_pk_add_f32 v[130:131], v[132:133], v[130:131]
	v_lshl_add_u64 v[134:135], v[146:147], 4, s[22:23]
	v_pk_fma_f32 v[130:131], v[130:131], s[28:29], v[168:169] op_sel_hi:[1,0,0]
	v_mov_b32_e32 v134, v204
	v_mov_b32_e32 v135, v205
	v_mov_b32_e32 v136, v206
	v_mov_b32_e32 v137, v207
	v_mul_f32_e32 v132, 0x4b800000, v131
	v_cmp_gt_f32_e64 s[0:1], s88, v131
	v_cmp_gt_f32_e32 vcc, s88, v130
	s_waitcnt vmcnt(0)
; template <int MODE>
; __device__ __forceinline__ void epi_scaled(Acc& acc, int pm, int pn, const float* ssq, const float* rq, const float* rkv, bf16_t* out, int ldo) {
;     ...
;         for (int m = 0; m < 4; ++m) {
;             const int row = pm * 256 + ai * 128 + t.wr * 64 + m * 16 + t.fr;
;             if (MODE == 1) rsv[ai][m] = (pn < 3) ? rq[row] : rkv[row];
;             else rsv[ai][m] = rstd_from_ssq(ssq, row);
;         }
; #pragma unroll
;     for (int ai = 0; ai < 2; ++ai)
; #pragma unroll
;         for (int m = 0; m < 4; ++m) {
;             int row = pm * 256 + ai * 128 + t.wr * 64 + m * 16 + t.fr;
;             const float rs = rsv[ai][m];
; #pragma unroll
;             for (int bj = 0; bj < 2; ++bj)
; #pragma unroll
;                 for (int n = 0; n < 2; ++n) {
;                     f32x4 v = acc[ai][bj][m][n] * rs;
	v_mov_b32_e32 v138, v134
	v_cndmask_b32_e64 v131, v131, v132, s[0:1]
	v_rsq_f32_e32 v131, v131
	v_mov_b32_e32 v134, v136
	v_mul_f32_e32 v132, 0x45800000, v131
	v_cndmask_b32_e64 v156, v131, v132, s[0:1]
	v_mul_f32_e32 v131, 0x4b800000, v130
	v_cndmask_b32_e32 v130, v130, v131, vcc
	v_rsq_f32_e32 v130, v130
	v_pk_mul_f32 v[94:95], v[94:95], v[156:157] op_sel_hi:[1,0]
	v_pk_mul_f32 v[90:91], v[90:91], v[156:157] op_sel_hi:[1,0]
	v_pk_mul_f32 v[86:87], v[86:87], v[156:157] op_sel_hi:[1,0]
	v_mul_f32_e32 v131, 0x45800000, v130
	v_cndmask_b32_e32 v150, v130, v131, vcc
	v_lshl_add_u64 v[130:131], v[152:153], 4, s[22:23]
	v_mov_b32_e32 v130, v208
	v_mov_b32_e32 v131, v209
	v_mov_b32_e32 v132, v210
	v_mov_b32_e32 v133, v211
	v_pk_mul_f32 v[82:83], v[82:83], v[156:157] op_sel_hi:[1,0]
	v_pk_mul_f32 v[78:79], v[78:79], v[150:151] op_sel_hi:[1,0]
	v_pk_mul_f32 v[74:75], v[74:75], v[150:151] op_sel_hi:[1,0]
	v_pk_mul_f32 v[70:71], v[70:71], v[150:151] op_sel_hi:[1,0]
	v_pk_mul_f32 v[66:67], v[66:67], v[150:151] op_sel_hi:[1,0]
	v_pk_mul_f32 v[84:85], v[84:85], v[156:157] op_sel_hi:[1,0]
	v_pk_mul_f32 v[68:69], v[68:69], v[150:151] op_sel_hi:[1,0]
	v_pk_mul_f32 v[96:97], v[96:97], v[156:157] op_sel_hi:[1,0]
	v_pk_mul_f32 v[92:93], v[92:93], v[156:157] op_sel_hi:[1,0]
	v_pk_mul_f32 v[88:89], v[88:89], v[156:157] op_sel_hi:[1,0]
	v_pk_mul_f32 v[80:81], v[80:81], v[150:151] op_sel_hi:[1,0]
	v_pk_mul_f32 v[76:77], v[76:77], v[150:151] op_sel_hi:[1,0]
	v_pk_mul_f32 v[72:73], v[72:73], v[150:151] op_sel_hi:[1,0]
	s_waitcnt vmcnt(0)
	v_mov_b32_e32 v139, v130
	v_mov_b32_e32 v130, v135
	v_pk_add_f32 v[130:131], v[138:139], v[130:131]
	v_mov_b32_e32 v135, v132
	v_pk_add_f32 v[130:131], v[134:135], v[130:131]
	v_mov_b32_e32 v132, v137
	v_pk_add_f32 v[130:131], v[132:133], v[130:131]
	v_add_u32_e32 v138, 0xb0, v166
	v_pk_fma_f32 v[130:131], v[130:131], s[28:29], v[168:169] op_sel_hi:[1,0,0]
	v_ashrrev_i32_e32 v139, 31, v138
	v_mul_f32_e32 v132, 0x4b800000, v131
	v_cmp_gt_f32_e64 s[0:1], s88, v131
	v_cmp_gt_f32_e32 vcc, s88, v130
	v_lshl_add_u64 v[134:135], v[138:139], 4, s[22:23]
	v_cndmask_b32_e64 v131, v131, v132, s[0:1]
	v_rsq_f32_e32 v131, v131
	v_mov_b32_e32 v134, v212
	v_mov_b32_e32 v135, v213
	v_mov_b32_e32 v136, v214
	v_mov_b32_e32 v137, v215
	v_mul_f32_e32 v132, 0x45800000, v131
	v_cndmask_b32_e64 v148, v131, v132, s[0:1]
	v_mul_f32_e32 v131, 0x4b800000, v130
	v_cndmask_b32_e32 v130, v130, v131, vcc
	v_rsq_f32_e32 v130, v130
	v_pk_mul_f32 v[62:63], v[62:63], v[148:149] op_sel_hi:[1,0]
	v_pk_mul_f32 v[58:59], v[58:59], v[148:149] op_sel_hi:[1,0]
	v_pk_mul_f32 v[54:55], v[54:55], v[148:149] op_sel_hi:[1,0]
	v_mul_f32_e32 v131, 0x45800000, v130
	v_cndmask_b32_e32 v140, v130, v131, vcc
	v_lshl_add_u64 v[130:131], v[142:143], 4, s[22:23]
	v_mov_b32_e32 v130, v216
	v_mov_b32_e32 v131, v217
	v_mov_b32_e32 v132, v218
	v_mov_b32_e32 v133, v219
	v_pk_mul_f32 v[50:51], v[50:51], v[148:149] op_sel_hi:[1,0]
	v_pk_mul_f32 v[46:47], v[46:47], v[140:141] op_sel_hi:[1,0]
	v_pk_mul_f32 v[42:43], v[42:43], v[140:141] op_sel_hi:[1,0]
	v_pk_mul_f32 v[38:39], v[38:39], v[140:141] op_sel_hi:[1,0]
	v_pk_mul_f32 v[34:35], v[34:35], v[140:141] op_sel_hi:[1,0]
	v_pk_mul_f32 v[52:53], v[52:53], v[148:149] op_sel_hi:[1,0]
	v_pk_mul_f32 v[36:37], v[36:37], v[140:141] op_sel_hi:[1,0]
	v_pk_mul_f32 v[64:65], v[64:65], v[148:149] op_sel_hi:[1,0]
	v_pk_mul_f32 v[60:61], v[60:61], v[148:149] op_sel_hi:[1,0]
	v_pk_mul_f32 v[56:57], v[56:57], v[148:149] op_sel_hi:[1,0]
	v_pk_mul_f32 v[48:49], v[48:49], v[140:141] op_sel_hi:[1,0]
	v_pk_mul_f32 v[44:45], v[44:45], v[140:141] op_sel_hi:[1,0]
	v_pk_mul_f32 v[40:41], v[40:41], v[140:141] op_sel_hi:[1,0]
	s_waitcnt vmcnt(0)
	v_mov_b32_e32 v170, v134
	v_mov_b32_e32 v134, v136
	v_mov_b32_e32 v171, v130
	v_mov_b32_e32 v130, v135
	v_pk_add_f32 v[130:131], v[170:171], v[130:131]
	v_mov_b32_e32 v135, v132
	v_pk_add_f32 v[130:131], v[134:135], v[130:131]
	v_mov_b32_e32 v132, v137
	v_pk_add_f32 v[130:131], v[132:133], v[130:131]
	s_nop 0
	v_pk_fma_f32 v[130:131], v[130:131], s[28:29], v[168:169] op_sel_hi:[1,0,0]
	s_nop 0
	v_mul_f32_e32 v132, 0x4b800000, v131
	v_cmp_gt_f32_e64 s[0:1], s88, v131
	v_cmp_gt_f32_e32 vcc, s88, v130
	s_nop 0
	v_cndmask_b32_e64 v131, v131, v132, s[0:1]
	v_rsq_f32_e32 v131, v131
	s_nop 0
	v_mul_f32_e32 v132, 0x45800000, v131
	v_cndmask_b32_e64 v134, v131, v132, s[0:1]
	v_mul_f32_e32 v131, 0x4b800000, v130
	v_cndmask_b32_e32 v130, v130, v131, vcc
	v_rsq_f32_e32 v130, v130
	v_pk_mul_f32 v[30:31], v[30:31], v[134:135] op_sel_hi:[1,0]
	v_pk_mul_f32 v[26:27], v[26:27], v[134:135] op_sel_hi:[1,0]
	v_pk_mul_f32 v[22:23], v[22:23], v[134:135] op_sel_hi:[1,0]
	v_mul_f32_e32 v131, 0x45800000, v130
	v_cndmask_b32_e32 v130, v130, v131, vcc
	v_lshrrev_b32_e32 v131, 1, v1
	v_mul_f32_e32 v1, 0xbfb8aa3b, v126
	v_mul_f32_e32 v126, 0xbfb8aa3b, v127
	v_exp_f32_e32 v1, v1
	v_exp_f32_e32 v126, v126
	v_pk_mul_f32 v[18:19], v[18:19], v[134:135] op_sel_hi:[1,0]
	v_pk_mul_f32 v[14:15], v[14:15], v[130:131] op_sel_hi:[1,0]
	v_add_f32_e32 v1, 1.0, v1
	v_add_f32_e32 v126, 1.0, v126
	v_rcp_f32_e32 v1, v1
	v_rcp_f32_e32 v126, v126
	v_pk_mul_f32 v[10:11], v[10:11], v[130:131] op_sel_hi:[1,0]
	v_pk_mul_f32 v[6:7], v[6:7], v[130:131] op_sel_hi:[1,0]
	s_lshl_b64 s[0:1], s[36:37], 1
	v_cvt_pk_bf16_f32 v126, v1, v126
	v_mul_f32_e32 v1, 0xbfb8aa3b, v122
	v_mul_f32_e32 v122, 0xbfb8aa3b, v123
	v_exp_f32_e32 v1, v1
	v_exp_f32_e32 v122, v122
	v_pk_mul_f32 v[20:21], v[20:21], v[134:135] op_sel_hi:[1,0]
	s_add_u32 s0, s70, s0
	v_add_f32_e32 v1, 1.0, v1
	v_add_f32_e32 v122, 1.0, v122
	v_rcp_f32_e32 v1, v1
	v_rcp_f32_e32 v122, v122
	v_pk_mul_f32 v[32:33], v[32:33], v[134:135] op_sel_hi:[1,0]
; __device__ __forceinline__ unsigned cvt_pk(float lo, float hi) { f32x2_t v = {lo, hi}; bf16x2_t b = __builtin_convertvector(v, bf16x2_t); return __builtin_bit_cast(unsigned, b); }
; __device__ __forceinline__ float sigmoidf_(float x) { return __builtin_amdgcn_rcpf(1.f + __builtin_amdgcn_exp2f(-1.4426950408889634f * x)); }
; template <int MODE>
; __device__ __forceinline__ void epi_scaled(Acc& acc, int pm, int pn, const float* ssq, const float* rq, const float* rkv, bf16_t* out, int ldo) {
;     ...
;                     if (MODE == 2) {
; #pragma unroll
;                         for (int j = 0; j < 4; ++j) v[j] = sigmoidf_(v[j]);
;                     }
;                     u32x2 w; w[0] = cvt_pk(v[0], v[1]); w[1] = cvt_pk(v[2], v[3]);
	v_pk_mul_f32 v[28:29], v[28:29], v[134:135] op_sel_hi:[1,0]
	v_pk_mul_f32 v[24:25], v[24:25], v[134:135] op_sel_hi:[1,0]
	v_cvt_pk_bf16_f32 v122, v1, v122
	v_mul_f32_e32 v1, 0xbfb8aa3b, v118
	v_mul_f32_e32 v118, 0xbfb8aa3b, v119
	v_exp_f32_e32 v1, v1
	v_exp_f32_e32 v118, v118
	v_pk_mul_f32 v[16:17], v[16:17], v[130:131] op_sel_hi:[1,0]
	v_pk_mul_f32 v[12:13], v[12:13], v[130:131] op_sel_hi:[1,0]
	v_add_f32_e32 v1, 1.0, v1
	v_add_f32_e32 v118, 1.0, v118
	v_rcp_f32_e32 v1, v1
	v_rcp_f32_e32 v118, v118
	v_pk_mul_f32 v[8:9], v[8:9], v[130:131] op_sel_hi:[1,0]
	v_pk_mul_f32 v[4:5], v[4:5], v[130:131] op_sel_hi:[1,0]
	v_pk_mul_f32 v[2:3], v[2:3], v[130:131] op_sel_hi:[1,0]
	v_cvt_pk_bf16_f32 v118, v1, v118
	v_mul_f32_e32 v1, 0xbfb8aa3b, v114
	v_mul_f32_e32 v114, 0xbfb8aa3b, v115
	v_exp_f32_e32 v1, v1
	v_exp_f32_e32 v114, v114
	v_mul_f32_e32 v115, 0xbfb8aa3b, v116
	v_mul_f32_e32 v116, 0xbfb8aa3b, v117
	v_add_f32_e32 v1, 1.0, v1
	v_add_f32_e32 v114, 1.0, v114
	v_rcp_f32_e32 v1, v1
	v_rcp_f32_e32 v114, v114
	v_exp_f32_e32 v115, v115
	v_exp_f32_e32 v116, v116
	s_addc_u32 s1, s71, s1
	v_cvt_pk_bf16_f32 v114, v1, v114
	v_mul_f32_e32 v1, 0xbfb8aa3b, v110
	v_mul_f32_e32 v110, 0xbfb8aa3b, v111
	v_exp_f32_e32 v1, v1
	v_exp_f32_e32 v110, v110
	v_add_f32_e32 v115, 1.0, v115
	v_add_f32_e32 v116, 1.0, v116
	v_add_f32_e32 v1, 1.0, v1
	v_add_f32_e32 v110, 1.0, v110
	v_rcp_f32_e32 v1, v1
	v_rcp_f32_e32 v110, v110
	v_rcp_f32_e32 v115, v115
	v_rcp_f32_e32 v116, v116
	v_mul_f32_e32 v127, 0xbfb8aa3b, v128
	v_cvt_pk_bf16_f32 v110, v1, v110
	v_mul_f32_e32 v1, 0xbfb8aa3b, v106
	v_mul_f32_e32 v106, 0xbfb8aa3b, v107
	v_exp_f32_e32 v1, v1
	v_exp_f32_e32 v106, v106
	v_mul_f32_e32 v128, 0xbfb8aa3b, v129
	v_mul_f32_e32 v123, 0xbfb8aa3b, v124
	v_add_f32_e32 v1, 1.0, v1
	v_add_f32_e32 v106, 1.0, v106
	v_rcp_f32_e32 v1, v1
	v_rcp_f32_e32 v106, v106
	v_mul_f32_e32 v124, 0xbfb8aa3b, v125
	v_mul_f32_e32 v119, 0xbfb8aa3b, v120
	v_mul_f32_e32 v120, 0xbfb8aa3b, v121
	v_cvt_pk_bf16_f32 v106, v1, v106
	v_mul_f32_e32 v1, 0xbfb8aa3b, v102
	v_mul_f32_e32 v102, 0xbfb8aa3b, v103
	v_exp_f32_e32 v1, v1
	v_exp_f32_e32 v102, v102
	v_mul_f32_e32 v111, 0xbfb8aa3b, v112
	v_mul_f32_e32 v112, 0xbfb8aa3b, v113
	v_add_f32_e32 v1, 1.0, v1
	v_add_f32_e32 v102, 1.0, v102
	v_rcp_f32_e32 v1, v1
	v_rcp_f32_e32 v102, v102
	v_mul_f32_e32 v107, 0xbfb8aa3b, v108
	v_mul_f32_e32 v108, 0xbfb8aa3b, v109
	v_mul_f32_e32 v103, 0xbfb8aa3b, v104
	v_cvt_pk_bf16_f32 v102, v1, v102
	v_mul_f32_e32 v1, 0xbfb8aa3b, v98
	v_mul_f32_e32 v98, 0xbfb8aa3b, v99
	v_exp_f32_e32 v1, v1
	v_exp_f32_e32 v98, v98
	v_mul_f32_e32 v99, 0xbfb8aa3b, v100
	v_mul_f32_e32 v100, 0xbfb8aa3b, v101
	v_add_f32_e32 v1, 1.0, v1
	v_add_f32_e32 v98, 1.0, v98
	v_rcp_f32_e32 v1, v1
	v_rcp_f32_e32 v98, v98
	v_exp_f32_e32 v99, v99
	v_exp_f32_e32 v100, v100
	v_mul_f32_e32 v104, 0xbfb8aa3b, v105
	v_cvt_pk_bf16_f32 v98, v1, v98
	v_mul_f32_e32 v1, 0xbfb8aa3b, v94
	v_mul_f32_e32 v94, 0xbfb8aa3b, v95
	v_exp_f32_e32 v1, v1
	v_exp_f32_e32 v94, v94
	v_add_f32_e32 v99, 1.0, v99
	v_add_f32_e32 v100, 1.0, v100
	v_add_f32_e32 v1, 1.0, v1
	v_add_f32_e32 v94, 1.0, v94
	v_rcp_f32_e32 v1, v1
	v_rcp_f32_e32 v94, v94
	v_rcp_f32_e32 v99, v99
	v_rcp_f32_e32 v100, v100
	v_mul_f32_e32 v95, 0xbfb8aa3b, v96
	v_cvt_pk_bf16_f32 v94, v1, v94
	v_mul_f32_e32 v1, 0xbfb8aa3b, v90
	v_mul_f32_e32 v90, 0xbfb8aa3b, v91
	v_exp_f32_e32 v1, v1
	v_exp_f32_e32 v90, v90
	v_mul_f32_e32 v96, 0xbfb8aa3b, v97
	v_mul_f32_e32 v91, 0xbfb8aa3b, v92
	v_add_f32_e32 v1, 1.0, v1
	v_add_f32_e32 v90, 1.0, v90
	v_rcp_f32_e32 v1, v1
	v_rcp_f32_e32 v90, v90
	v_mul_f32_e32 v92, 0xbfb8aa3b, v93
	v_lshl_add_u64 v[132:133], s[0:1], 0, v[144:145]
	v_and_b32_e32 v144, 24, v131
	v_cvt_pk_bf16_f32 v90, v1, v90
	v_mul_f32_e32 v1, 0xbfb8aa3b, v86
	v_mul_f32_e32 v86, 0xbfb8aa3b, v87
	v_exp_f32_e32 v1, v1
	v_exp_f32_e32 v86, v86
	v_mul_f32_e32 v87, 0xbfb8aa3b, v88
	v_mul_f32_e32 v88, 0xbfb8aa3b, v89
	v_add_f32_e32 v1, 1.0, v1
	v_add_f32_e32 v86, 1.0, v86
	v_rcp_f32_e32 v1, v1
	v_rcp_f32_e32 v86, v86
	v_exp_f32_e32 v127, v127
	v_exp_f32_e32 v128, v128
	v_exp_f32_e32 v123, v123
	v_cvt_pk_bf16_f32 v86, v1, v86
	v_mul_f32_e32 v1, 0xbfb8aa3b, v82
	v_mul_f32_e32 v82, 0xbfb8aa3b, v83
	v_exp_f32_e32 v1, v1
	v_exp_f32_e32 v82, v82
	v_mul_f32_e32 v83, 0xbfb8aa3b, v84
	v_mul_f32_e32 v84, 0xbfb8aa3b, v85
	v_add_f32_e32 v1, 1.0, v1
	v_add_f32_e32 v82, 1.0, v82
	v_rcp_f32_e32 v1, v1
	v_rcp_f32_e32 v82, v82
	v_exp_f32_e32 v83, v83
	v_exp_f32_e32 v84, v84
	v_exp_f32_e32 v124, v124
	v_cvt_pk_bf16_f32 v82, v1, v82
	v_mul_f32_e32 v1, 0xbfb8aa3b, v78
	v_mul_f32_e32 v78, 0xbfb8aa3b, v79
	v_exp_f32_e32 v1, v1
	v_exp_f32_e32 v78, v78
	v_add_f32_e32 v83, 1.0, v83
	v_add_f32_e32 v84, 1.0, v84
	v_add_f32_e32 v1, 1.0, v1
	v_add_f32_e32 v78, 1.0, v78
	v_rcp_f32_e32 v1, v1
	v_rcp_f32_e32 v78, v78
	v_mul_f32_e32 v79, 0xbfb8aa3b, v80
	v_mul_f32_e32 v80, 0xbfb8aa3b, v81
	v_exp_f32_e32 v119, v119
	v_cvt_pk_bf16_f32 v78, v1, v78
	v_mul_f32_e32 v1, 0xbfb8aa3b, v74
	v_mul_f32_e32 v74, 0xbfb8aa3b, v75
	v_exp_f32_e32 v1, v1
	v_exp_f32_e32 v74, v74
	v_mul_f32_e32 v75, 0xbfb8aa3b, v76
	v_mul_f32_e32 v76, 0xbfb8aa3b, v77
	v_add_f32_e32 v1, 1.0, v1
	v_add_f32_e32 v74, 1.0, v74
	v_rcp_f32_e32 v1, v1
	v_rcp_f32_e32 v74, v74
	v_exp_f32_e32 v120, v120
	v_exp_f32_e32 v111, v111
	v_exp_f32_e32 v112, v112
	v_cvt_pk_bf16_f32 v74, v1, v74
	v_mul_f32_e32 v1, 0xbfb8aa3b, v70
	v_mul_f32_e32 v70, 0xbfb8aa3b, v71
	v_exp_f32_e32 v1, v1
	v_exp_f32_e32 v70, v70
	v_mul_f32_e32 v71, 0xbfb8aa3b, v72
	v_mul_f32_e32 v72, 0xbfb8aa3b, v73
	v_add_f32_e32 v1, 1.0, v1
	v_add_f32_e32 v70, 1.0, v70
	v_rcp_f32_e32 v1, v1
	v_rcp_f32_e32 v70, v70
	v_exp_f32_e32 v107, v107
	v_exp_f32_e32 v108, v108
; __device__ __forceinline__ unsigned cvt_pk(float lo, float hi) { f32x2_t v = {lo, hi}; bf16x2_t b = __builtin_convertvector(v, bf16x2_t); return __builtin_bit_cast(unsigned, b); }
; __device__ __forceinline__ float sigmoidf_(float x) { return __builtin_amdgcn_rcpf(1.f + __builtin_amdgcn_exp2f(-1.4426950408889634f * x)); }
; template <int MODE>
; __device__ __forceinline__ void epi_scaled(Acc& acc, int pm, int pn, const float* ssq, const float* rq, const float* rkv, bf16_t* out, int ldo) {
;     ...
;                     if (MODE == 2) {
; #pragma unroll
;                         for (int j = 0; j < 4; ++j) v[j] = sigmoidf_(v[j]);
;                     }
;                     u32x2 w; w[0] = cvt_pk(v[0], v[1]); w[1] = cvt_pk(v[2], v[3]);
	v_exp_f32_e32 v103, v103
	v_cvt_pk_bf16_f32 v70, v1, v70
	v_mul_f32_e32 v1, 0xbfb8aa3b, v66
	v_mul_f32_e32 v66, 0xbfb8aa3b, v67
	v_exp_f32_e32 v1, v1
	v_exp_f32_e32 v66, v66
	v_mul_f32_e32 v67, 0xbfb8aa3b, v68
	v_mul_f32_e32 v68, 0xbfb8aa3b, v69
	v_add_f32_e32 v1, 1.0, v1
	v_add_f32_e32 v66, 1.0, v66
	v_rcp_f32_e32 v1, v1
	v_rcp_f32_e32 v66, v66
	v_exp_f32_e32 v67, v67
	v_exp_f32_e32 v68, v68
	v_exp_f32_e32 v104, v104
	v_cvt_pk_bf16_f32 v66, v1, v66
	v_mul_f32_e32 v1, 0xbfb8aa3b, v62
	v_mul_f32_e32 v62, 0xbfb8aa3b, v63
	v_exp_f32_e32 v1, v1
	v_exp_f32_e32 v62, v62
	v_mul_f32_e32 v63, 0xbfb8aa3b, v64
	v_mul_f32_e32 v64, 0xbfb8aa3b, v65
	v_add_f32_e32 v1, 1.0, v1
	v_add_f32_e32 v62, 1.0, v62
	v_rcp_f32_e32 v1, v1
	v_rcp_f32_e32 v62, v62
	v_exp_f32_e32 v95, v95
	v_exp_f32_e32 v96, v96
	v_exp_f32_e32 v91, v91
	v_cvt_pk_bf16_f32 v62, v1, v62
	v_mul_f32_e32 v1, 0xbfb8aa3b, v58
	v_mul_f32_e32 v58, 0xbfb8aa3b, v59
	v_exp_f32_e32 v1, v1
	v_exp_f32_e32 v58, v58
	v_mul_f32_e32 v59, 0xbfb8aa3b, v60
	v_mul_f32_e32 v60, 0xbfb8aa3b, v61
	v_add_f32_e32 v1, 1.0, v1
	v_add_f32_e32 v58, 1.0, v58
	v_rcp_f32_e32 v1, v1
	v_rcp_f32_e32 v58, v58
	v_exp_f32_e32 v92, v92
	v_exp_f32_e32 v87, v87
	v_exp_f32_e32 v88, v88
	v_cvt_pk_bf16_f32 v58, v1, v58
	v_mul_f32_e32 v1, 0xbfb8aa3b, v54
	v_mul_f32_e32 v54, 0xbfb8aa3b, v55
	v_exp_f32_e32 v1, v1
	v_exp_f32_e32 v54, v54
	v_mul_f32_e32 v55, 0xbfb8aa3b, v56
	v_mul_f32_e32 v56, 0xbfb8aa3b, v57
	v_add_f32_e32 v1, 1.0, v1
	v_add_f32_e32 v54, 1.0, v54
	v_rcp_f32_e32 v1, v1
	v_rcp_f32_e32 v54, v54
	v_rcp_f32_e32 v83, v83
	v_rcp_f32_e32 v84, v84
	v_exp_f32_e32 v79, v79
	v_cvt_pk_bf16_f32 v54, v1, v54
	v_mul_f32_e32 v1, 0xbfb8aa3b, v50
	v_mul_f32_e32 v50, 0xbfb8aa3b, v51
	v_exp_f32_e32 v1, v1
	v_exp_f32_e32 v50, v50
	v_mul_f32_e32 v51, 0xbfb8aa3b, v52
	v_mul_f32_e32 v52, 0xbfb8aa3b, v53
	v_add_f32_e32 v1, 1.0, v1
	v_add_f32_e32 v50, 1.0, v50
	v_rcp_f32_e32 v1, v1
	v_rcp_f32_e32 v50, v50
	v_exp_f32_e32 v51, v51
	v_exp_f32_e32 v52, v52
	v_exp_f32_e32 v80, v80
	v_cvt_pk_bf16_f32 v50, v1, v50
	v_mul_f32_e32 v1, 0xbfb8aa3b, v46
	v_mul_f32_e32 v46, 0xbfb8aa3b, v47
	v_exp_f32_e32 v1, v1
	v_exp_f32_e32 v46, v46
	v_mul_f32_e32 v47, 0xbfb8aa3b, v48
	v_mul_f32_e32 v48, 0xbfb8aa3b, v49
	v_add_f32_e32 v1, 1.0, v1
	v_add_f32_e32 v46, 1.0, v46
	v_rcp_f32_e32 v1, v1
	v_rcp_f32_e32 v46, v46
	v_exp_f32_e32 v75, v75
	v_exp_f32_e32 v76, v76
	v_exp_f32_e32 v71, v71
	v_cvt_pk_bf16_f32 v46, v1, v46
	v_mul_f32_e32 v1, 0xbfb8aa3b, v42
	v_mul_f32_e32 v42, 0xbfb8aa3b, v43
	v_exp_f32_e32 v1, v1
	v_exp_f32_e32 v42, v42
	v_mul_f32_e32 v43, 0xbfb8aa3b, v44
	v_mul_f32_e32 v44, 0xbfb8aa3b, v45
	v_add_f32_e32 v1, 1.0, v1
	v_add_f32_e32 v42, 1.0, v42
	v_rcp_f32_e32 v1, v1
	v_rcp_f32_e32 v42, v42
	v_exp_f32_e32 v72, v72
	v_add_f32_e32 v67, 1.0, v67
	v_add_f32_e32 v68, 1.0, v68
	v_cvt_pk_bf16_f32 v42, v1, v42
	v_mul_f32_e32 v1, 0xbfb8aa3b, v38
	v_mul_f32_e32 v38, 0xbfb8aa3b, v39
	v_exp_f32_e32 v1, v1
	v_exp_f32_e32 v38, v38
	v_mul_f32_e32 v39, 0xbfb8aa3b, v40
	v_mul_f32_e32 v40, 0xbfb8aa3b, v41
	v_add_f32_e32 v1, 1.0, v1
	v_add_f32_e32 v38, 1.0, v38
	v_rcp_f32_e32 v1, v1
	v_rcp_f32_e32 v38, v38
	v_exp_f32_e32 v63, v63
	v_exp_f32_e32 v64, v64
	v_exp_f32_e32 v59, v59
	v_cvt_pk_bf16_f32 v38, v1, v38
	v_mul_f32_e32 v1, 0xbfb8aa3b, v34
	v_mul_f32_e32 v34, 0xbfb8aa3b, v35
	v_exp_f32_e32 v1, v1
	v_exp_f32_e32 v34, v34
	v_mul_f32_e32 v35, 0xbfb8aa3b, v36
	v_mul_f32_e32 v36, 0xbfb8aa3b, v37
	v_add_f32_e32 v1, 1.0, v1
	v_add_f32_e32 v34, 1.0, v34
	v_rcp_f32_e32 v1, v1
	v_rcp_f32_e32 v34, v34
	v_exp_f32_e32 v35, v35
	v_exp_f32_e32 v36, v36
	v_exp_f32_e32 v60, v60
	v_cvt_pk_bf16_f32 v34, v1, v34
	v_mul_f32_e32 v1, 0xbfb8aa3b, v30
	v_mul_f32_e32 v30, 0xbfb8aa3b, v31
	v_exp_f32_e32 v1, v1
	v_exp_f32_e32 v30, v30
	v_mul_f32_e32 v31, 0xbfb8aa3b, v32
	v_mul_f32_e32 v32, 0xbfb8aa3b, v33
	v_add_f32_e32 v1, 1.0, v1
	v_add_f32_e32 v30, 1.0, v30
	v_rcp_f32_e32 v1, v1
	v_rcp_f32_e32 v30, v30
	v_exp_f32_e32 v55, v55
	v_exp_f32_e32 v56, v56
	v_exp_f32_e32 v47, v47
	v_cvt_pk_bf16_f32 v30, v1, v30
	v_mul_f32_e32 v1, 0xbfb8aa3b, v26
	v_mul_f32_e32 v26, 0xbfb8aa3b, v27
	v_exp_f32_e32 v1, v1
	v_exp_f32_e32 v26, v26
	v_mul_f32_e32 v27, 0xbfb8aa3b, v28
	v_mul_f32_e32 v28, 0xbfb8aa3b, v29
	v_add_f32_e32 v1, 1.0, v1
	v_add_f32_e32 v26, 1.0, v26
	v_rcp_f32_e32 v1, v1
	v_rcp_f32_e32 v26, v26
	v_exp_f32_e32 v48, v48
	v_exp_f32_e32 v43, v43
	v_exp_f32_e32 v44, v44
	v_cvt_pk_bf16_f32 v26, v1, v26
	v_mul_f32_e32 v1, 0xbfb8aa3b, v22
	v_mul_f32_e32 v22, 0xbfb8aa3b, v23
	v_exp_f32_e32 v1, v1
	v_exp_f32_e32 v22, v22
	v_mul_f32_e32 v23, 0xbfb8aa3b, v24
	v_mul_f32_e32 v24, 0xbfb8aa3b, v25
	v_add_f32_e32 v1, 1.0, v1
	v_add_f32_e32 v22, 1.0, v22
	v_rcp_f32_e32 v1, v1
	v_rcp_f32_e32 v22, v22
	v_exp_f32_e32 v39, v39
	v_exp_f32_e32 v40, v40
	v_exp_f32_e32 v31, v31
	v_cvt_pk_bf16_f32 v22, v1, v22
	v_mul_f32_e32 v1, 0xbfb8aa3b, v18
	v_mul_f32_e32 v18, 0xbfb8aa3b, v19
	v_exp_f32_e32 v1, v1
	v_exp_f32_e32 v18, v18
	v_mul_f32_e32 v19, 0xbfb8aa3b, v20
	v_mul_f32_e32 v20, 0xbfb8aa3b, v21
	v_add_f32_e32 v1, 1.0, v1
	v_add_f32_e32 v18, 1.0, v18
	v_rcp_f32_e32 v1, v1
	v_rcp_f32_e32 v18, v18
	v_exp_f32_e32 v19, v19
	v_exp_f32_e32 v20, v20
	v_exp_f32_e32 v32, v32
	v_cvt_pk_bf16_f32 v18, v1, v18
	v_mul_f32_e32 v1, 0xbfb8aa3b, v14
	v_mul_f32_e32 v14, 0xbfb8aa3b, v15
	v_exp_f32_e32 v1, v1
	v_exp_f32_e32 v14, v14
	v_mul_f32_e32 v15, 0xbfb8aa3b, v16
	v_mul_f32_e32 v16, 0xbfb8aa3b, v17
	v_add_f32_e32 v1, 1.0, v1
	v_add_f32_e32 v14, 1.0, v14
	v_rcp_f32_e32 v1, v1
	v_rcp_f32_e32 v14, v14
	v_exp_f32_e32 v27, v27
	v_exp_f32_e32 v28, v28
	v_exp_f32_e32 v23, v23
	v_cvt_pk_bf16_f32 v14, v1, v14
	v_mul_f32_e32 v1, 0xbfb8aa3b, v10
; __device__ __forceinline__ unsigned cvt_pk(float lo, float hi) { f32x2_t v = {lo, hi}; bf16x2_t b = __builtin_convertvector(v, bf16x2_t); return __builtin_bit_cast(unsigned, b); }
; __device__ __forceinline__ float sigmoidf_(float x) { return __builtin_amdgcn_rcpf(1.f + __builtin_amdgcn_exp2f(-1.4426950408889634f * x)); }
; template <int MODE>
; __device__ __forceinline__ void epi_scaled(Acc& acc, int pm, int pn, const float* ssq, const float* rq, const float* rkv, bf16_t* out, int ldo) {
;     ...
;                     if (MODE == 2) {
; #pragma unroll
;                         for (int j = 0; j < 4; ++j) v[j] = sigmoidf_(v[j]);
;                     }
;                     u32x2 w; w[0] = cvt_pk(v[0], v[1]); w[1] = cvt_pk(v[2], v[3]);
;                     *(u32x2*)(out + (size_t)row * ldo + pn * 256 + bj * 128 + t.wc * 32 + n * 16 + t.fq * 4) = w;
;                 }
	v_mul_f32_e32 v10, 0xbfb8aa3b, v11
	v_exp_f32_e32 v1, v1
	v_exp_f32_e32 v10, v10
	v_mul_f32_e32 v11, 0xbfb8aa3b, v12
	v_mul_f32_e32 v12, 0xbfb8aa3b, v13
	v_add_f32_e32 v1, 1.0, v1
	v_add_f32_e32 v10, 1.0, v10
	v_rcp_f32_e32 v1, v1
	v_rcp_f32_e32 v10, v10
	v_exp_f32_e32 v24, v24
	v_exp_f32_e32 v15, v15
	v_exp_f32_e32 v16, v16
	v_cvt_pk_bf16_f32 v10, v1, v10
	v_mul_f32_e32 v1, 0xbfb8aa3b, v6
	v_mul_f32_e32 v6, 0xbfb8aa3b, v7
	v_exp_f32_e32 v1, v1
	v_exp_f32_e32 v6, v6
	v_mul_f32_e32 v7, 0xbfb8aa3b, v8
	v_mul_f32_e32 v8, 0xbfb8aa3b, v9
	v_add_f32_e32 v1, 1.0, v1
	v_add_f32_e32 v6, 1.0, v6
	v_rcp_f32_e32 v1, v1
	v_rcp_f32_e32 v6, v6
	v_exp_f32_e32 v11, v11
	v_exp_f32_e32 v12, v12
	v_exp_f32_e32 v7, v7
	v_cvt_pk_bf16_f32 v6, v1, v6
	v_mul_f32_e32 v1, 0xbfb8aa3b, v2
	v_mul_f32_e32 v2, 0xbfb8aa3b, v3
	v_mul_f32_e32 v3, 0xbfb8aa3b, v4
	v_mul_f32_e32 v4, 0xbfb8aa3b, v5
	v_exp_f32_e32 v8, v8
	v_exp_f32_e32 v1, v1
	v_exp_f32_e32 v2, v2
	v_exp_f32_e32 v3, v3
	v_exp_f32_e32 v4, v4
	v_lshl_add_u64 v[132:133], v[132:133], 0, v[144:145]
	v_rcp_f32_e32 v67, v67
	v_rcp_f32_e32 v68, v68
	v_add_f32_e32 v51, 1.0, v51
	v_add_f32_e32 v52, 1.0, v52
	v_mad_i64_i32 v[136:137], s[0:1], v166, s84, v[132:133]
	v_cvt_pk_bf16_f32 v115, v115, v116
	v_rcp_f32_e32 v51, v51
	v_rcp_f32_e32 v52, v52
	v_add_f32_e32 v35, 1.0, v35
	v_add_f32_e32 v36, 1.0, v36
	global_store_dwordx2 v[136:137], v[114:115], off offset:288
	v_mad_i64_i32 v[114:115], s[0:1], v162, s84, v[132:133]
	v_cvt_pk_bf16_f32 v99, v99, v100
	v_rcp_f32_e32 v35, v35
	v_rcp_f32_e32 v36, v36
	v_add_f32_e32 v19, 1.0, v19
	v_add_f32_e32 v20, 1.0, v20
	v_add_f32_e32 v127, 1.0, v127
	v_add_f32_e32 v128, 1.0, v128
	v_add_f32_e32 v123, 1.0, v123
	v_add_f32_e32 v124, 1.0, v124
	v_add_f32_e32 v119, 1.0, v119
	v_add_f32_e32 v120, 1.0, v120
	v_add_f32_e32 v111, 1.0, v111
	v_add_f32_e32 v112, 1.0, v112
	v_add_f32_e32 v107, 1.0, v107
	v_add_f32_e32 v108, 1.0, v108
	v_add_f32_e32 v103, 1.0, v103
	v_add_f32_e32 v104, 1.0, v104
	global_store_dwordx2 v[114:115], v[98:99], off offset:288
	v_mad_i64_i32 v[98:99], s[0:1], v160, s84, v[132:133]
	v_add_f32_e32 v95, 1.0, v95
	v_add_f32_e32 v96, 1.0, v96
	v_add_f32_e32 v91, 1.0, v91
	v_add_f32_e32 v92, 1.0, v92
	v_add_f32_e32 v87, 1.0, v87
	v_add_f32_e32 v88, 1.0, v88
	v_cvt_pk_bf16_f32 v83, v83, v84
	v_add_f32_e32 v79, 1.0, v79
	v_add_f32_e32 v80, 1.0, v80
	v_add_f32_e32 v75, 1.0, v75
	v_add_f32_e32 v76, 1.0, v76
	v_add_f32_e32 v71, 1.0, v71
	v_add_f32_e32 v72, 1.0, v72
	v_add_f32_e32 v63, 1.0, v63
	v_add_f32_e32 v64, 1.0, v64
	v_add_f32_e32 v59, 1.0, v59
	v_add_f32_e32 v60, 1.0, v60
	v_add_f32_e32 v55, 1.0, v55
	v_add_f32_e32 v56, 1.0, v56
	v_add_f32_e32 v47, 1.0, v47
	v_add_f32_e32 v48, 1.0, v48
	v_add_f32_e32 v43, 1.0, v43
	v_add_f32_e32 v44, 1.0, v44
	v_add_f32_e32 v39, 1.0, v39
	v_add_f32_e32 v40, 1.0, v40
	v_add_f32_e32 v31, 1.0, v31
	v_add_f32_e32 v32, 1.0, v32
	v_add_f32_e32 v27, 1.0, v27
	v_add_f32_e32 v28, 1.0, v28
	v_add_f32_e32 v23, 1.0, v23
	v_add_f32_e32 v24, 1.0, v24
	v_rcp_f32_e32 v19, v19
	v_rcp_f32_e32 v20, v20
	v_add_f32_e32 v15, 1.0, v15
	v_add_f32_e32 v16, 1.0, v16
	v_add_f32_e32 v11, 1.0, v11
	v_add_f32_e32 v12, 1.0, v12
	v_add_f32_e32 v7, 1.0, v7
	v_add_f32_e32 v8, 1.0, v8
	v_add_f32_e32 v1, 1.0, v1
	v_add_f32_e32 v2, 1.0, v2
	v_add_f32_e32 v3, 1.0, v3
	v_add_f32_e32 v4, 1.0, v4
	v_rcp_f32_e32 v127, v127
	v_rcp_f32_e32 v128, v128
	v_rcp_f32_e32 v123, v123
	v_rcp_f32_e32 v124, v124
	v_rcp_f32_e32 v119, v119
	v_rcp_f32_e32 v120, v120
	v_rcp_f32_e32 v111, v111
	v_rcp_f32_e32 v112, v112
	v_rcp_f32_e32 v107, v107
	v_rcp_f32_e32 v108, v108
	v_rcp_f32_e32 v103, v103
	v_rcp_f32_e32 v104, v104
	v_rcp_f32_e32 v95, v95
	v_rcp_f32_e32 v96, v96
	v_rcp_f32_e32 v91, v91
	v_rcp_f32_e32 v92, v92
	v_rcp_f32_e32 v87, v87
	v_rcp_f32_e32 v88, v88
; __device__ __forceinline__ unsigned cvt_pk(float lo, float hi) { f32x2_t v = {lo, hi}; bf16x2_t b = __builtin_convertvector(v, bf16x2_t); return __builtin_bit_cast(unsigned, b); }
; __device__ __forceinline__ float sigmoidf_(float x) { return __builtin_amdgcn_rcpf(1.f + __builtin_amdgcn_exp2f(-1.4426950408889634f * x)); }
; template <int MODE>
; __device__ __forceinline__ void epi_scaled(Acc& acc, int pm, int pn, const float* ssq, const float* rq, const float* rkv, bf16_t* out, int ldo) {
;     ...
;             for (int bj = 0; bj < 2; ++bj)
; #pragma unroll
;                 for (int n = 0; n < 2; ++n) {
;                     f32x4 v = acc[ai][bj][m][n] * rs;
;                     if (MODE == 2) {
; #pragma unroll
;                         for (int j = 0; j < 4; ++j) v[j] = sigmoidf_(v[j]);
;                     }
;                     u32x2 w; w[0] = cvt_pk(v[0], v[1]); w[1] = cvt_pk(v[2], v[3]);
;                     *(u32x2*)(out + (size_t)row * ldo + pn * 256 + bj * 128 + t.wc * 32 + n * 16 + t.fq * 4) = w;
;                 }
; __device__ __forceinline__ void phase_gates(const Ctx& a, LAS unsigned char* lds) {
;     ...
;         __syncthreads();
	global_store_dwordx2 v[98:99], v[82:83], off offset:288
	v_mad_i64_i32 v[82:83], s[0:1], v154, s84, v[132:133]
	v_rcp_f32_e32 v79, v79
	v_rcp_f32_e32 v80, v80
	v_rcp_f32_e32 v75, v75
	v_rcp_f32_e32 v76, v76
	v_rcp_f32_e32 v71, v71
	v_rcp_f32_e32 v72, v72
	v_cvt_pk_bf16_f32 v67, v67, v68
	v_rcp_f32_e32 v63, v63
	v_rcp_f32_e32 v64, v64
	v_rcp_f32_e32 v59, v59
	v_rcp_f32_e32 v60, v60
	v_rcp_f32_e32 v55, v55
	v_rcp_f32_e32 v56, v56
	v_rcp_f32_e32 v47, v47
	v_rcp_f32_e32 v48, v48
	v_rcp_f32_e32 v43, v43
	v_rcp_f32_e32 v44, v44
	v_rcp_f32_e32 v39, v39
	v_rcp_f32_e32 v40, v40
	v_rcp_f32_e32 v31, v31
	v_rcp_f32_e32 v32, v32
	v_rcp_f32_e32 v27, v27
	v_rcp_f32_e32 v28, v28
	v_rcp_f32_e32 v23, v23
	v_rcp_f32_e32 v24, v24
	v_rcp_f32_e32 v15, v15
	v_rcp_f32_e32 v16, v16
	v_rcp_f32_e32 v11, v11
	v_rcp_f32_e32 v12, v12
	v_rcp_f32_e32 v7, v7
	v_rcp_f32_e32 v8, v8
	v_rcp_f32_e32 v1, v1
	v_rcp_f32_e32 v2, v2
	v_rcp_f32_e32 v3, v3
	v_rcp_f32_e32 v4, v4
	global_store_dwordx2 v[82:83], v[66:67], off offset:288
	v_mad_i64_i32 v[66:67], s[0:1], v152, s84, v[132:133]
	v_cvt_pk_bf16_f32 v51, v51, v52
	global_store_dwordx2 v[66:67], v[50:51], off offset:288
	v_mad_i64_i32 v[50:51], s[0:1], v146, s84, v[132:133]
	v_cvt_pk_bf16_f32 v35, v35, v36
	global_store_dwordx2 v[50:51], v[34:35], off offset:288
	v_mad_i64_i32 v[34:35], s[0:1], v142, s84, v[132:133]
	v_cvt_pk_bf16_f32 v19, v19, v20
	v_cvt_pk_bf16_f32 v127, v127, v128
	v_cvt_pk_bf16_f32 v123, v123, v124
	v_cvt_pk_bf16_f32 v119, v119, v120
	v_cvt_pk_bf16_f32 v111, v111, v112
	v_cvt_pk_bf16_f32 v107, v107, v108
	v_cvt_pk_bf16_f32 v103, v103, v104
	v_cvt_pk_bf16_f32 v95, v95, v96
	v_cvt_pk_bf16_f32 v91, v91, v92
	v_cvt_pk_bf16_f32 v87, v87, v88
	v_cvt_pk_bf16_f32 v79, v79, v80
	v_cvt_pk_bf16_f32 v75, v75, v76
	v_cvt_pk_bf16_f32 v71, v71, v72
	v_cvt_pk_bf16_f32 v63, v63, v64
	v_cvt_pk_bf16_f32 v59, v59, v60
	v_cvt_pk_bf16_f32 v55, v55, v56
	v_cvt_pk_bf16_f32 v47, v47, v48
	v_cvt_pk_bf16_f32 v43, v43, v44
	v_cvt_pk_bf16_f32 v39, v39, v40
	v_cvt_pk_bf16_f32 v31, v31, v32
	v_cvt_pk_bf16_f32 v27, v27, v28
	v_cvt_pk_bf16_f32 v23, v23, v24
	global_store_dwordx2 v[34:35], v[18:19], off offset:288
	v_mad_i64_i32 v[18:19], s[0:1], v138, s84, v[132:133]
	v_cvt_pk_bf16_f32 v15, v15, v16
	v_cvt_pk_bf16_f32 v11, v11, v12
	v_cvt_pk_bf16_f32 v7, v7, v8
	v_cvt_pk_bf16_f32 v2, v1, v2
	v_cvt_pk_bf16_f32 v3, v3, v4
	s_and_b64 vcc, exec, s[12:13]
	global_store_dwordx2 v[136:137], v[126:127], off
	global_store_dwordx2 v[136:137], v[122:123], off offset:32
	global_store_dwordx2 v[136:137], v[118:119], off offset:256
	global_store_dwordx2 v[114:115], v[110:111], off
	global_store_dwordx2 v[114:115], v[106:107], off offset:32
	global_store_dwordx2 v[114:115], v[102:103], off offset:256
	global_store_dwordx2 v[98:99], v[94:95], off
	global_store_dwordx2 v[98:99], v[90:91], off offset:32
	global_store_dwordx2 v[98:99], v[86:87], off offset:256
	global_store_dwordx2 v[82:83], v[78:79], off
	global_store_dwordx2 v[82:83], v[74:75], off offset:32
	global_store_dwordx2 v[82:83], v[70:71], off offset:256
	global_store_dwordx2 v[66:67], v[62:63], off
	global_store_dwordx2 v[66:67], v[58:59], off offset:32
	global_store_dwordx2 v[66:67], v[54:55], off offset:256
	global_store_dwordx2 v[50:51], v[46:47], off
	global_store_dwordx2 v[50:51], v[42:43], off offset:32
	global_store_dwordx2 v[50:51], v[38:39], off offset:256
	global_store_dwordx2 v[34:35], v[30:31], off
	global_store_dwordx2 v[34:35], v[26:27], off offset:32
	global_store_dwordx2 v[34:35], v[22:23], off offset:256
	global_store_dwordx2 v[18:19], v[14:15], off
	global_store_dwordx2 v[18:19], v[10:11], off offset:32
	global_store_dwordx2 v[18:19], v[6:7], off offset:256
	global_store_dwordx2 v[18:19], v[2:3], off offset:288
	s_waitcnt lgkmcnt(0)
	s_barrier
	s_cbranch_vccnz .LBB0_691
